# GDN prep: l2norm lane reductions via DPP (no LDS round trips), gate-stage parameter loads issued together
# speedup vs baseline: 1.0078x; 1.0055x over previous
; DI void gdn_prep_item(const Params& P, int l, int n, int hh, char* smem) {
;     ...
;   if (w == 0) {
;     const int t = lane; const float a_raw = ab[(size_t)(t0 + t) * 16 + hh], b_raw = ab[(size_t)(t0 + t) * 16 + 8 + hh];
;     const float Aa = __expf(P.gdn_a_log[l * 8 + hh]); const float xb = a_raw + P.gdn_dt_bias[l * 8 + hh];
;     const float ex = __expf(fminf(xb, 20.f));
;     const float sp = xb > 20.f ? xb : (ex < 0.01f ? ex * (1.f - ex * (0.5f - ex * (1.f / 3.f))) : __logf(1.f + ex));
.LBB0_419:
	v_mov_b32_e32 v82, v206
	global_load_dwordx2 v[50:51], v1, s[40:41] offset:1224
	s_ashr_i32 s12, s17, 3
	s_and_b32 s18, s17, 7
	s_lshl_b32 s2, s18, 8
	s_ashr_i32 s3, s12, 31
	s_add_u32 s8, s2, s12
	s_addc_u32 s9, 0, s3
	v_cmp_lt_u32_e32 vcc, 63, v82
	s_and_saveexec_b64 s[2:3], vcc
	s_xor_b64 s[2:3], exec, s[2:3]
	v_mbcnt_hi_u32_b32 v84, -1, v207
	v_and_b32_e32 v81, 64, v84
	s_or_saveexec_b64 s[10:11], s[2:3]
	s_lshl_b32 s19, s12, 6
	v_and_b32_e32 v34, 63, v82
	s_xor_b64 exec, exec, s[10:11]
	s_cbranch_execz .LBB0_431
	global_load_dwordx4 v[10:13], v1, s[40:41] offset:1104
	v_or_b32_e32 v2, s19, v82
	v_ashrrev_i32_e32 v3, 31, v2
	v_lshlrev_b64 v[2:3], 6, v[2:3]
	s_waitcnt vmcnt(0)
	v_lshl_add_u64 v[2:3], v[50:51], 0, v[2:3]
	s_lshl_b32 s62, s18, 2
	v_lshl_add_u64 v[2:3], v[2:3], 0, s[62:63]
	s_mov_b64 s[2:3], 0x262e8000
	v_lshl_add_u64 v[4:5], v[2:3], 0, s[2:3]
	v_add_co_u32_e32 v2, vcc, 0x262e8000, v2
	s_or_b32 s62, s18, s16
	s_nop 0
	v_addc_co_u32_e32 v3, vcc, 0, v3, vcc
	global_load_dword v6, v[2:3], off
	global_load_dword v0, v[4:5], off offset:32
	s_lshl_b64 s[2:3], s[62:63], 2
	v_lshl_add_u64 v[14:15], v[10:11], 0, s[2:3]
	v_lshl_add_u64 v[16:17], v[12:13], 0, s[2:3]
	global_load_dword v2, v[14:15], off
	s_mov_b32 s2, 0x41a00000
	global_load_dword v3, v[16:17], off
	s_waitcnt vmcnt(0) lgkmcnt(0)
	v_add_f32_e32 v3, v6, v3
	v_cmp_nlt_f32_e32 vcc, s2, v3
	s_and_saveexec_b64 s[12:13], vcc
	s_cbranch_execz .LBB0_428
	v_max_f32_e32 v3, v3, v3
	v_min_f32_e32 v3, 0x41a00000, v3
	v_mul_f32_e32 v3, 0x3fb8aa3b, v3
	v_exp_f32_e32 v4, v3
	s_mov_b32 s2, 0x3c23d70a
	v_cmp_ngt_f32_e32 vcc, s2, v4
	s_and_saveexec_b64 s[2:3], vcc
	s_xor_b64 s[14:15], exec, s[2:3]
	s_cbranch_execz .LBB0_425
	v_add_f32_e32 v3, 1.0, v4
	v_cmp_gt_f32_e32 vcc, s84, v3
	s_mov_b32 s2, 0x3f317217
	s_nop 0
	v_cndmask_b32_e64 v4, 0, 32, vcc
	v_ldexp_f32 v3, v3, v4
	v_log_f32_e32 v3, v3
	s_nop 0
	v_mul_f32_e32 v4, 0x3f317217, v3
	v_fma_f32 v4, v3, s2, -v4
	v_fmac_f32_e32 v4, 0x3377d1cf, v3
	s_mov_b32 s2, 0x7f800000
	v_fmac_f32_e32 v4, 0x3f317217, v3
	v_cmp_lt_f32_e64 s[2:3], |v3|, s2
	s_nop 1
	v_cndmask_b32_e64 v3, v3, v4, s[2:3]
	v_mov_b32_e32 v4, 0x41b17218
	v_cndmask_b32_e32 v4, 0, v4, vcc
	v_sub_f32_e32 v3, v3, v4

; DI void gdn_prep_item(const Params& P, int l, int n, int hh, char* smem) {
;     ...
;   __syncthreads();
;   {
;     const int t = tid >> 3, part = tid & 7, tabs = t0 + t;
;     const float gct = gcs[t], egct = gcs[128 + t], ktl = __expf(gcs[63] - gct);
;     const int pjt = 32 * (t >> 5) + perm32(t & 31);
; #pragma unroll
;     for (int X = 0; X < 3; ++X) {
;       const int cb = X * 1024 + hh * 128 + part * 16;
;       float y[16];
; #pragma unroll
;       for (int e = 0; e < 16; ++e) y[e] = 0.f;
;       u32x4 pv[4][2]; f32x4 wv[4][4];
; #pragma unroll
;       for (int j = 0; j < 4; ++j) { const int row = tabs - 3 + j, rr = row < 0 ? 0 : row;
;         pv[j][0] = *(const u32x4*)(proj + (size_t)rr * DINP + cb); pv[j][1] = *(const u32x4*)(proj + (size_t)rr * DINP + cb + 8);
;         const float* cw = P.gdn_conv + ((size_t)l * 4 + j) * 3072 + cb;
; #pragma unroll
;         for (int e4 = 0; e4 < 4; ++e4) wv[j][e4] = *(const f32x4*)(cw + 4 * e4); }
.LBB0_431:
	s_or_b64 exec, exec, s[10:11]
	s_waitcnt lgkmcnt(0)
	s_barrier
	global_load_dwordx2 v[38:39], v1, s[40:41] offset:1096
	v_ashrrev_i32_e32 v63, 3, v82
	s_lshl_b64 s[2:3], s[8:9], 14
	v_and_b32_e32 v79, 7, v82
	s_lshl_b32 s10, s18, 7
	v_lshlrev_b32_e32 v2, 7, v63
	s_waitcnt vmcnt(0)
	v_lshl_add_u64 v[54:55], v[50:51], 0, s[2:3]
	v_lshlrev_b32_e32 v58, 5, v79
	v_lshl_or_b32 v74, v79, 4, s10
	v_ashrrev_i32_e32 v3, 31, v2
	v_lshlrev_b32_e32 v4, 3, v82
	v_mov_b32_e32 v41, v1
	v_and_b32_e32 v0, 0xc0, v58
	v_lshlrev_b32_e32 v40, 2, v74
	v_lshl_add_u64 v[2:3], v[2:3], 1, v[54:55]
	v_add_u32_e32 v65, s19, v63
	v_lshl_add_u64 v[2:3], v[2:3], 0, v[0:1]
	v_and_b32_e32 v0, 8, v4
	v_lshl_add_u64 v[56:57], v[50:51], 0, s[30:31]
	v_max_i32_e32 v5, 3, v65
	v_max_i32_e32 v6, 2, v65
	v_max_i32_e32 v7, 1, v65
	v_lshl_add_u64 v[36:37], v[2:3], 0, v[0:1]
	v_lshlrev_b32_e32 v0, 1, v74
	s_movk_i32 s10, 0x6000
	v_max_i32_e32 v75, 0, v65
	v_add_u32_e32 v78, -3, v5
	v_add_u32_e32 v77, -2, v6
	v_add_u32_e32 v76, -1, v7
	v_lshl_add_u64 v[2:3], v[56:57], 0, v[0:1]
	v_mad_u64_u32 v[6:7], s[2:3], v78, s81, v[2:3]
	v_mad_u64_u32 v[10:11], s[2:3], v77, s81, v[2:3]
	v_mad_u64_u32 v[14:15], s[2:3], v76, s81, v[2:3]
	v_mad_u64_u32 v[30:31], s[2:3], v75, s81, v[2:3]
	s_mov_b64 s[12:13], 0x6000
	s_mov_b64 s[14:15], 0x9000
	s_mov_b32 s18, 0x9000
	global_load_dwordx4 v[2:5], v[6:7], off
	global_load_dwordx4 v[18:21], v[6:7], off offset:16
	s_nop 0
	global_load_dwordx4 v[6:9], v[10:11], off
	global_load_dwordx4 v[22:25], v[10:11], off offset:16
	s_nop 0
	global_load_dwordx4 v[10:13], v[14:15], off
	global_load_dwordx4 v[26:29], v[14:15], off offset:16
	s_nop 0
	global_load_dwordx4 v[14:17], v[30:31], off
	s_nop 0
	global_load_dwordx4 v[30:33], v[30:31], off offset:16
	v_lshl_add_u32 v35, v63, 2, v241
	s_lshl_b64 s[8:9], s[8:9], 13
	v_lshrrev_b32_e32 v59, 5, v34
	s_mov_b64 s[2:3], 0x252e8000
	s_movk_i32 s11, 0x110
	v_lshl_add_u64 v[38:39], v[38:39], 0, v[40:41]
	v_lshl_add_u64 v[40:41], v[38:39], 0, s[0:1]
	v_add_co_u32_e32 v52, vcc, s10, v40
	v_lshl_add_u64 v[38:39], v[38:39], 0, s[4:5]
	s_nop 0
	v_addc_co_u32_e32 v53, vcc, 0, v41, vcc
	global_load_dwordx4 v[42:45], v[40:41], off
	global_load_dwordx4 v[86:89], v[40:41], off offset:16
	global_load_dwordx4 v[90:93], v[40:41], off offset:32
	global_load_dwordx4 v[46:49], v[40:41], off offset:48
	global_load_dwordx4 v[70:73], v[38:39], off
	global_load_dwordx4 v[94:97], v[38:39], off offset:16
	global_load_dwordx4 v[98:101], v[38:39], off offset:32
	global_load_dwordx4 v[66:69], v[38:39], off offset:48
	v_lshl_add_u64 v[38:39], v[40:41], 0, s[12:13]
	v_lshl_add_u64 v[60:61], v[40:41], 0, s[14:15]
	v_add_co_u32_e32 v40, vcc, s18, v40
	s_nop 1
	v_addc_co_u32_e32 v41, vcc, 0, v41, vcc
	global_load_dwordx4 v[102:105], v[38:39], off offset:16
	global_load_dwordx4 v[106:109], v[38:39], off offset:32
	global_load_dwordx4 v[110:113], v[52:53], off
	global_load_dwordx4 v[114:117], v[38:39], off offset:48
	global_load_dwordx4 v[118:121], v[60:61], off offset:16
	global_load_dwordx4 v[122:125], v[60:61], off offset:32
	global_load_dwordx4 v[126:129], v[40:41], off
	global_load_dwordx4 v[130:133], v[60:61], off offset:48
	ds_read2st64_b32 v[40:41], v35 offset1:2
	v_mov_b32_e32 v35, 0x1c8fc
	ds_read_b32 v38, v35
	v_lshl_add_u64 v[34:35], v[50:51], 0, s[8:9]
	v_lshl_add_u64 v[52:53], v[34:35], 0, s[2:3]
	v_and_b32_e32 v61, 31, v82
	s_waitcnt lgkmcnt(0)
	v_sub_f32_e32 v34, v38, v40
	v_mul_f32_e32 v34, 0x3fb8aa3b, v34
	v_exp_f32_e32 v40, v34
	v_lshlrev_b32_e32 v34, 1, v63
	v_and_b32_e32 v38, 24, v34
	v_lshrrev_b32_e32 v34, 2, v63
	v_and_b32_e32 v39, 4, v34
	v_mad_u64_u32 v[34:35], s[2:3], v63, s11, v[58:59]
	v_lshlrev_b32_e32 v35, 9, v63
	v_lshl_or_b32 v80, v79, 6, v35
	v_and_b32_e32 v35, 0xffffffe3, v63
	s_mov_b64 s[2:3], 0x1f2e8000
	v_or3_b32 v35, v38, v35, v39
	v_lshl_add_u64 v[38:39], v[36:37], 0, s[2:3]
	v_add_u32_e32 v83, 0x10800, v80
	v_cmp_lt_i32_e32 vcc, 2, v65
	v_xor_b32_e32 v85, 1, v84
	v_add_u32_e32 v142, 64, v81
	v_cndmask_b32_e64 v58, 0, 1.0, vcc
	v_cmp_lt_i32_e32 vcc, 1, v65
	s_waitcnt vmcnt(0)
	v_pk_mul_f32 v[138:139], v[58:59], v[48:49] op_sel_hi:[0,1]
	v_pk_mul_f32 v[140:141], v[58:59], v[46:47] op_sel_hi:[0,1]
	v_cndmask_b32_e64 v60, 0, 1.0, vcc
	v_cmp_lt_i32_e32 vcc, 0, v65
	v_pk_mul_f32 v[134:135], v[60:61], v[68:69] op_sel_hi:[0,1]
	v_pk_mul_f32 v[68:69], v[60:61], v[72:73] op_sel_hi:[0,1]
	v_cndmask_b32_e64 v62, 0, 1.0, vcc
	v_cmp_lt_i32_e32 vcc, -1, v65
	v_pk_mul_f32 v[116:117], v[62:63], v[116:117] op_sel_hi:[0,1]
	v_pk_mul_f32 v[136:137], v[60:61], v[66:67] op_sel_hi:[0,1]
	v_cndmask_b32_e64 v64, 0, 1.0, vcc
	v_pk_mul_f32 v[72:73], v[64:65], v[128:129] op_sel_hi:[0,1]
	v_lshlrev_b32_e32 v128, 16, v21
	v_and_b32_e32 v129, 0xffff0000, v21
	v_pk_mul_f32 v[48:49], v[64:65], v[126:127] op_sel_hi:[0,1]
	v_lshlrev_b32_e32 v126, 16, v25
	v_and_b32_e32 v127, 0xffff0000, v25
	v_pk_fma_f32 v[128:129], v[138:139], v[128:129], 0 op_sel_hi:[1,1,0]
	v_pk_mul_f32 v[66:67], v[58:59], v[44:45] op_sel_hi:[0,1]
	v_pk_mul_f32 v[44:45], v[60:61], v[70:71] op_sel_hi:[0,1]
	v_pk_mul_f32 v[70:71], v[62:63], v[112:113] op_sel_hi:[0,1]
	v_pk_mul_f32 v[112:113], v[64:65], v[118:119] op_sel_hi:[0,1]
	v_pk_mul_f32 v[118:119], v[64:65], v[124:125] op_sel_hi:[0,1]
	v_lshlrev_b32_e32 v124, 16, v29
	v_and_b32_e32 v125, 0xffff0000, v29
	v_pk_fma_f32 v[126:127], v[134:135], v[126:127], v[128:129]
	v_pk_mul_f32 v[132:133], v[64:65], v[132:133] op_sel_hi:[0,1]
	v_pk_mul_f32 v[46:47], v[62:63], v[110:111] op_sel_hi:[0,1]
	v_pk_mul_f32 v[110:111], v[64:65], v[120:121] op_sel_hi:[0,1]
	v_pk_mul_f32 v[120:121], v[64:65], v[122:123] op_sel_hi:[0,1]
; DI void unpack8(const u32x4& v, float* f) { f[0] = bflo(v.x); f[1] = bfhi(v.x); f[2] = bflo(v.y); f[3] = bfhi(v.y); f[4] = bflo(v.z); f[5] = bfhi(v.z); f[6] = bflo(v.w); f[7] = bfhi(v.w); }
; DI float silu_f(float x) { return x * __builtin_amdgcn_rcpf(1.f + __expf(-x)); }
; DI void gdn_prep_item(const Params& P, int l, int n, int hh, char* smem) {
;     ...
;       __builtin_amdgcn_sched_barrier(0);
; #pragma unroll
;       for (int j = 0; j < 4; ++j) { const float msk = (tabs - 3 + j) >= 0 ? 1.f : 0.f;
;         float xv[16]; unpack8(pv[j][0], xv); unpack8(pv[j][1], xv + 8);
; #pragma unroll
;         for (int e4 = 0; e4 < 4; ++e4) { const f32x4 wm = wv[j][e4] * msk; y[4 * e4] += wm.x * xv[4 * e4]; y[4 * e4 + 1] += wm.y * xv[4 * e4 + 1]; y[4 * e4 + 2] += wm.z * xv[4 * e4 + 2]; y[4 * e4 + 3] += wm.w * xv[4 * e4 + 3]; } }
; #pragma unroll
;       for (int e = 0; e < 16; ++e) y[e] = silu_f(y[e]);
	v_lshlrev_b32_e32 v122, 16, v33
	v_and_b32_e32 v123, 0xffff0000, v33
	v_pk_fma_f32 v[116:117], v[116:117], v[124:125], v[126:127]
	v_cmp_lt_i32_e32 vcc, v85, v142
	v_pk_fma_f32 v[116:117], v[132:133], v[122:123], v[116:117]
	v_lshlrev_b32_e32 v122, 16, v32
	v_mul_f32_e32 v25, 0xbfb8aa3b, v116
	v_exp_f32_e32 v25, v25
	v_cndmask_b32_e32 v81, v84, v85, vcc
	v_and_b32_e32 v123, 0xffff0000, v32
	v_lshlrev_b32_e32 v32, 16, v28
	v_add_f32_e32 v85, 1.0, v25
	v_and_b32_e32 v33, 0xffff0000, v28
	v_lshlrev_b32_e32 v28, 16, v24
	v_and_b32_e32 v29, 0xffff0000, v24
	v_lshlrev_b32_e32 v24, 16, v20
	v_and_b32_e32 v25, 0xffff0000, v20
	v_pk_fma_f32 v[24:25], v[140:141], v[24:25], 0 op_sel_hi:[1,1,0]
	v_pk_mul_f32 v[114:115], v[62:63], v[114:115] op_sel_hi:[0,1]
	v_pk_fma_f32 v[24:25], v[136:137], v[28:29], v[24:25]
	v_pk_mul_f32 v[130:131], v[64:65], v[130:131] op_sel_hi:[0,1]
	v_pk_fma_f32 v[24:25], v[114:115], v[32:33], v[24:25]
	v_mul_f32_e32 v21, 0xbfb8aa3b, v117
	v_pk_fma_f32 v[24:25], v[130:131], v[122:123], v[24:25]
	v_exp_f32_e32 v21, v21
	v_mul_f32_e32 v20, 0xbfb8aa3b, v24
	v_exp_f32_e32 v28, v20
	v_mul_f32_e32 v20, 0xbfb8aa3b, v25
	v_exp_f32_e32 v29, v20
	v_add_f32_e32 v21, 1.0, v21
	v_rcp_f32_e32 v21, v21
	v_rcp_f32_e32 v20, v85
	v_add_f32_e32 v28, 1.0, v28
	v_add_f32_e32 v29, 1.0, v29
	v_rcp_f32_e32 v28, v28
	v_rcp_f32_e32 v29, v29
	v_pk_mul_f32 v[92:93], v[58:59], v[92:93] op_sel_hi:[0,1]
	v_lshlrev_b32_e32 v122, 16, v19
	v_and_b32_e32 v123, 0xffff0000, v19
	v_pk_mul_f32 v[100:101], v[60:61], v[100:101] op_sel_hi:[0,1]
	v_pk_mul_f32 v[20:21], v[116:117], v[20:21]
	v_lshlrev_b32_e32 v116, 16, v23
	v_and_b32_e32 v117, 0xffff0000, v23
	v_pk_fma_f32 v[92:93], v[92:93], v[122:123], 0 op_sel_hi:[1,1,0]
	v_pk_mul_f32 v[108:109], v[62:63], v[108:109] op_sel_hi:[0,1]
	v_lshlrev_b32_e32 v114, 16, v27
	v_and_b32_e32 v115, 0xffff0000, v27
	v_pk_fma_f32 v[92:93], v[100:101], v[116:117], v[92:93]
	v_pk_mul_f32 v[24:25], v[24:25], v[28:29]
	v_lshlrev_b32_e32 v28, 16, v31
	v_and_b32_e32 v29, 0xffff0000, v31
	v_pk_fma_f32 v[92:93], v[108:109], v[114:115], v[92:93]
	v_pk_mul_f32 v[90:91], v[58:59], v[90:91] op_sel_hi:[0,1]
	v_pk_fma_f32 v[28:29], v[118:119], v[28:29], v[92:93]
	v_lshlrev_b32_e32 v108, 16, v30
	v_mul_f32_e32 v19, 0xbfb8aa3b, v28
	v_exp_f32_e32 v19, v19
	v_mul_f32_e32 v23, 0xbfb8aa3b, v29
	v_exp_f32_e32 v23, v23
	v_and_b32_e32 v109, 0xffff0000, v30
	v_add_f32_e32 v19, 1.0, v19
	v_rcp_f32_e32 v100, v19
	v_add_f32_e32 v19, 1.0, v23
	v_lshlrev_b32_e32 v30, 16, v26
	v_and_b32_e32 v31, 0xffff0000, v26
	v_lshlrev_b32_e32 v26, 16, v22
	v_and_b32_e32 v27, 0xffff0000, v22
	v_lshlrev_b32_e32 v22, 16, v18
	v_and_b32_e32 v23, 0xffff0000, v18
	v_pk_mul_f32 v[98:99], v[60:61], v[98:99] op_sel_hi:[0,1]
	v_rcp_f32_e32 v101, v19
	v_pk_fma_f32 v[18:19], v[90:91], v[22:23], 0 op_sel_hi:[1,1,0]
	v_pk_mul_f32 v[106:107], v[62:63], v[106:107] op_sel_hi:[0,1]
	v_pk_fma_f32 v[18:19], v[98:99], v[26:27], v[18:19]
	v_pk_mul_f32 v[88:89], v[58:59], v[88:89] op_sel_hi:[0,1]
	v_pk_fma_f32 v[18:19], v[106:107], v[30:31], v[18:19]
	v_lshlrev_b32_e32 v98, 16, v5
	v_pk_fma_f32 v[18:19], v[120:121], v[108:109], v[18:19]
	v_and_b32_e32 v99, 0xffff0000, v5
	v_pk_mul_f32 v[96:97], v[60:61], v[96:97] op_sel_hi:[0,1]
	v_mul_f32_e32 v22, 0xbfb8aa3b, v18
	v_lshlrev_b32_e32 v90, 16, v9
	v_and_b32_e32 v91, 0xffff0000, v9
	v_pk_fma_f32 v[88:89], v[88:89], v[98:99], 0 op_sel_hi:[1,1,0]
	v_pk_mul_f32 v[104:105], v[62:63], v[104:105] op_sel_hi:[0,1]
	v_exp_f32_e32 v26, v22
	v_mul_f32_e32 v22, 0xbfb8aa3b, v19
	v_lshlrev_b32_e32 v30, 16, v13
	v_and_b32_e32 v31, 0xffff0000, v13
	v_pk_fma_f32 v[88:89], v[96:97], v[90:91], v[88:89]
	v_exp_f32_e32 v27, v22
	v_pk_mul_f32 v[22:23], v[28:29], v[100:101]
	v_lshlrev_b32_e32 v28, 16, v17
	v_and_b32_e32 v29, 0xffff0000, v17
	v_pk_fma_f32 v[30:31], v[104:105], v[30:31], v[88:89]
	v_pk_mul_f32 v[86:87], v[58:59], v[86:87] op_sel_hi:[0,1]
	v_pk_fma_f32 v[28:29], v[110:111], v[28:29], v[30:31]
	v_and_b32_e32 v17, 0xffff0000, v12
	v_mul_f32_e32 v5, 0xbfb8aa3b, v28
	v_exp_f32_e32 v5, v5
	v_mul_f32_e32 v9, 0xbfb8aa3b, v29
	v_exp_f32_e32 v9, v9
	v_and_b32_e32 v13, 0xffff0000, v8
	v_add_f32_e32 v5, 1.0, v5
	v_rcp_f32_e32 v30, v5
	v_add_f32_e32 v5, 1.0, v9
	v_rcp_f32_e32 v31, v5
	v_and_b32_e32 v9, 0xffff0000, v4
	v_pk_mul_f32 v[94:95], v[60:61], v[94:95] op_sel_hi:[0,1]
	v_pk_mul_f32 v[102:103], v[62:63], v[102:103] op_sel_hi:[0,1]
	v_pk_mul_f32 v[28:29], v[28:29], v[30:31]
	v_lshlrev_b32_e32 v30, 16, v16
	v_and_b32_e32 v31, 0xffff0000, v16
	v_lshlrev_b32_e32 v16, 16, v12
	v_lshlrev_b32_e32 v12, 16, v8
	v_lshlrev_b32_e32 v8, 16, v4
	v_pk_fma_f32 v[4:5], v[86:87], v[8:9], 0 op_sel_hi:[1,1,0]
	v_lshlrev_b32_e32 v90, 16, v3
	v_pk_fma_f32 v[4:5], v[94:95], v[12:13], v[4:5]
	v_and_b32_e32 v91, 0xffff0000, v3
	v_pk_fma_f32 v[4:5], v[102:103], v[16:17], v[4:5]
	v_lshlrev_b32_e32 v86, 16, v7
	v_pk_fma_f32 v[4:5], v[112:113], v[30:31], v[4:5]
	v_and_b32_e32 v87, 0xffff0000, v7
	v_mul_f32_e32 v8, 0xbfb8aa3b, v4
	v_exp_f32_e32 v12, v8
	v_mul_f32_e32 v8, 0xbfb8aa3b, v5
	v_exp_f32_e32 v13, v8
	v_pk_fma_f32 v[66:67], v[66:67], v[90:91], 0 op_sel_hi:[1,1,0]
	v_lshlrev_b32_e32 v30, 16, v11
	v_and_b32_e32 v31, 0xffff0000, v11
	v_pk_fma_f32 v[66:67], v[68:69], v[86:87], v[66:67]
	v_lshlrev_b32_e32 v16, 16, v15
	v_and_b32_e32 v17, 0xffff0000, v15
	v_pk_fma_f32 v[30:31], v[70:71], v[30:31], v[66:67]
	v_add_f32_e32 v12, 1.0, v12
	v_pk_fma_f32 v[16:17], v[72:73], v[16:17], v[30:31]
	v_add_f32_e32 v13, 1.0, v13
	v_mul_f32_e32 v3, 0xbfb8aa3b, v16
	v_mul_f32_e32 v7, 0xbfb8aa3b, v17
	v_rcp_f32_e32 v12, v12
	v_rcp_f32_e32 v13, v13
	v_exp_f32_e32 v3, v3
	v_exp_f32_e32 v7, v7
; DI unsigned pack2(float lo, float hi) { f32x2 v = {lo, hi}; bf2_t b = __builtin_convertvector(v, bf2_t); return __builtin_bit_cast(unsigned, b); }
; DI float silu_f(float x) { return x * __builtin_amdgcn_rcpf(1.f + __expf(-x)); }
; DI void gdn_prep_item(const Params& P, int l, int n, int hh, char* smem) {
;     ...
;       for (int e = 0; e < 16; ++e) y[e] = silu_f(y[e]);
;       if (X < 2) { float ss = 0.f;
; #pragma unroll
;         for (int e = 0; e < 16; ++e) ss += y[e] * y[e];
;         ss += __shfl_xor(ss, 1); ss += __shfl_xor(ss, 2); ss += __shfl_xor(ss, 4);
;         const float rn = rsqrtf(ss + EPS) * (X == 0 ? 0.08838834764831845f : 1.f);
; #pragma unroll
;         for (int e = 0; e < 16; ++e) y[e] *= rn; }
;       if (X == 0) {
;         u32x4 p0 = {pack2(y[0], y[1]), pack2(y[2], y[3]), pack2(y[4], y[5]), pack2(y[6], y[7])}, p1 = {pack2(y[8], y[9]), pack2(y[10], y[11]), pack2(y[12], y[13]), pack2(y[14], y[15])};
;         *(u32x4*)(qb16 + t * 272 + part * 32) = p0; *(u32x4*)(qb16 + t * 272 + part * 32 + 16) = p1;
; #pragma unroll
;         for (int b = 0; b < 4; ++b) { u32x2 pk = {pack2(y[4 * b] * egct, y[4 * b + 1] * egct), pack2(y[4 * b + 2] * egct, y[4 * b + 3] * egct)};
;           *(u32x2*)(Qd + t * 128 + 32 * (part >> 1) + 8 * b + 4 * (part & 1)) = pk; }
	v_pk_mul_f32 v[42:43], v[58:59], v[42:43] op_sel_hi:[0,1]
	v_pk_mul_f32 v[4:5], v[4:5], v[12:13]
	v_add_f32_e32 v3, 1.0, v3
	v_add_f32_e32 v13, 1.0, v7
	v_lshlrev_b32_e32 v30, 16, v14
	v_and_b32_e32 v31, 0xffff0000, v14
	v_lshlrev_b32_e32 v14, 16, v10
	v_and_b32_e32 v15, 0xffff0000, v10
	v_lshlrev_b32_e32 v10, 16, v6
	v_and_b32_e32 v11, 0xffff0000, v6
	v_lshlrev_b32_e32 v6, 16, v2
	v_and_b32_e32 v7, 0xffff0000, v2
	v_rcp_f32_e32 v12, v3
	v_pk_fma_f32 v[2:3], v[42:43], v[6:7], 0 op_sel_hi:[1,1,0]
	v_rcp_f32_e32 v13, v13
	v_pk_fma_f32 v[2:3], v[44:45], v[10:11], v[2:3]
	v_add_f32_e32 v26, 1.0, v26
	v_pk_fma_f32 v[2:3], v[46:47], v[14:15], v[2:3]
	v_pk_mul_f32 v[12:13], v[16:17], v[12:13]
	v_pk_fma_f32 v[2:3], v[48:49], v[30:31], v[2:3]
	v_add_f32_e32 v27, 1.0, v27
	v_mul_f32_e32 v6, 0xbfb8aa3b, v2
	v_mul_f32_e32 v7, 0xbfb8aa3b, v3
	v_exp_f32_e32 v6, v6
	v_exp_f32_e32 v7, v7
	v_pk_mul_f32 v[14:15], v[12:13], v[12:13]
	v_rcp_f32_e32 v26, v26
	v_add_f32_e32 v6, 1.0, v6
	v_add_f32_e32 v7, 1.0, v7
	v_rcp_f32_e32 v6, v6
	v_rcp_f32_e32 v7, v7
	v_rcp_f32_e32 v27, v27
	v_pk_mul_f32 v[10:11], v[4:5], v[4:5]
	v_pk_mul_f32 v[8:9], v[28:29], v[28:29]
	v_pk_mul_f32 v[2:3], v[2:3], v[6:7]
	v_pk_mul_f32 v[18:19], v[18:19], v[26:27]
	v_pk_mul_f32 v[6:7], v[2:3], v[2:3]
	v_pk_mul_f32 v[26:27], v[18:19], v[18:19]
	v_add_f32_e32 v6, v6, v7
	v_add_f32_e32 v6, v14, v6
	v_add_f32_e32 v6, v15, v6
	v_add_f32_e32 v6, v10, v6
	v_add_f32_e32 v6, v11, v6
	v_add_f32_e32 v6, v8, v6
	v_add_f32_e32 v6, v9, v6
	v_add_f32_e32 v6, v26, v6
	v_pk_mul_f32 v[88:89], v[22:23], v[22:23]
	v_add_f32_e32 v6, v27, v6
	v_add_f32_e32 v6, v88, v6
	v_pk_mul_f32 v[92:93], v[24:25], v[24:25]
	v_add_f32_e32 v6, v89, v6
	v_add_f32_e32 v6, v92, v6
	v_pk_mul_f32 v[32:33], v[20:21], v[20:21]
	v_add_f32_e32 v6, v93, v6
	v_add_f32_e32 v6, v32, v6
	v_lshlrev_b32_e32 v81, 2, v81
	v_add_f32_e32 v6, v33, v6
	s_nop 1
	v_xor_b32_e32 v8, 2, v84
	v_cmp_lt_i32_e32 vcc, v8, v142
	s_mov_b32 s2, 0x1f2e8000
	s_waitcnt lgkmcnt(0)
	v_add_f32_dpp v6, v6, v6 quad_perm:[1,0,3,2] row_mask:0xf bank_mask:0xf
	v_cndmask_b32_e32 v8, v84, v8, vcc
	v_lshlrev_b32_e32 v140, 2, v8
	s_nop 1
	v_xor_b32_e32 v8, 4, v84
	v_cmp_lt_i32_e32 vcc, v8, v142
	s_waitcnt lgkmcnt(0)
	v_add_f32_dpp v6, v6, v6 quad_perm:[2,3,0,1] row_mask:0xf bank_mask:0xf
	v_cndmask_b32_e32 v8, v84, v8, vcc
	v_lshlrev_b32_e32 v141, 2, v8
	s_nop 1
	v_mov_b32_dpp v7, v6 row_ror:4 row_mask:0xf bank_mask:0xa
	v_mov_b32_dpp v7, v6 row_ror:12 row_mask:0xf bank_mask:0x5
	s_waitcnt lgkmcnt(0)
	v_add_f32_e32 v6, v6, v7
	v_add_f32_e32 v6, 0x358637bd, v6
	v_mul_f32_e32 v7, 0x4b800000, v6
	v_cmp_gt_f32_e32 vcc, s84, v6
	s_nop 1
	v_cndmask_b32_e32 v6, v6, v7, vcc
	v_rsq_f32_e32 v6, v6
	s_nop 0
	v_mul_f32_e32 v7, 0x45800000, v6
	v_cndmask_b32_e32 v6, v6, v7, vcc
	v_mul_f32_e32 v6, 0x3db504f3, v6
	v_pk_mul_f32 v[10:11], v[2:3], v[6:7] op_sel_hi:[1,0]
	v_pk_mul_f32 v[12:13], v[12:13], v[6:7] op_sel_hi:[1,0]
	v_pk_mul_f32 v[14:15], v[4:5], v[6:7] op_sel_hi:[1,0]
	v_pk_mul_f32 v[16:17], v[28:29], v[6:7] op_sel_hi:[1,0]
	v_pk_mul_f32 v[18:19], v[18:19], v[6:7] op_sel_hi:[1,0]
	v_pk_mul_f32 v[22:23], v[22:23], v[6:7] op_sel_hi:[1,0]
	v_pk_mul_f32 v[24:25], v[24:25], v[6:7] op_sel_hi:[1,0]
	v_pk_mul_f32 v[20:21], v[20:21], v[6:7] op_sel_hi:[1,0]
	v_cvt_pk_bf16_f32 v2, v10, v11
	v_cvt_pk_bf16_f32 v3, v12, v13
	v_cvt_pk_bf16_f32 v4, v14, v15
	v_cvt_pk_bf16_f32 v5, v16, v17
	v_cvt_pk_bf16_f32 v6, v18, v19
	v_cvt_pk_bf16_f32 v7, v22, v23
	v_cvt_pk_bf16_f32 v8, v24, v25
	v_cvt_pk_bf16_f32 v9, v20, v21
	ds_write_b128 v34, v[2:5] offset:17408
	ds_write_b128 v34, v[6:9] offset:17424
	v_mov_b32_e32 v2, v41
	v_pk_mul_f32 v[4:5], v[2:3], v[10:11] op_sel_hi:[0,1]
	v_pk_mul_f32 v[6:7], v[2:3], v[12:13] op_sel_hi:[0,1]
	v_cvt_pk_bf16_f32 v4, v4, v5
	v_cvt_pk_bf16_f32 v5, v6, v7
	v_add_co_u32_e32 v6, vcc, s2, v36
	s_nop 1
	v_addc_co_u32_e32 v7, vcc, 0, v37, vcc
	global_store_dwordx2 v[6:7], v[4:5], off
	v_pk_mul_f32 v[4:5], v[2:3], v[14:15] op_sel_hi:[0,1]
	v_pk_mul_f32 v[6:7], v[2:3], v[16:17] op_sel_hi:[0,1]
	v_cvt_pk_bf16_f32 v4, v4, v5
	v_cvt_pk_bf16_f32 v5, v6, v7
	global_store_dwordx2 v[38:39], v[4:5], off offset:16
	v_pk_mul_f32 v[4:5], v[2:3], v[18:19] op_sel_hi:[0,1]
	v_pk_mul_f32 v[6:7], v[2:3], v[22:23] op_sel_hi:[0,1]
	v_cvt_pk_bf16_f32 v4, v4, v5
	v_cvt_pk_bf16_f32 v5, v6, v7
	global_store_dwordx2 v[38:39], v[4:5], off offset:32
	v_pk_mul_f32 v[4:5], v[2:3], v[24:25] op_sel_hi:[0,1]
	v_pk_mul_f32 v[2:3], v[2:3], v[20:21] op_sel_hi:[0,1]
	v_cvt_pk_bf16_f32 v4, v4, v5
	v_cvt_pk_bf16_f32 v5, v2, v3
	global_store_dwordx2 v[38:39], v[4:5], off offset:48
	global_load_dwordx2 v[2:3], v1, s[40:41] offset:1096
	v_or_b32_e32 v6, 0x400, v74
	v_lshlrev_b32_e32 v4, 2, v6
	v_mov_b32_e32 v5, v1
	v_lshlrev_b32_e32 v14, 1, v6
	v_mov_b32_e32 v15, v1
	s_waitcnt vmcnt(0)
; DI void unpack8(const u32x4& v, float* f) { f[0] = bflo(v.x); f[1] = bfhi(v.x); f[2] = bflo(v.y); f[3] = bfhi(v.y); f[4] = bflo(v.z); f[5] = bfhi(v.z); f[6] = bflo(v.w); f[7] = bfhi(v.w); }
; DI float silu_f(float x) { return x * __builtin_amdgcn_rcpf(1.f + __expf(-x)); }
; DI void gdn_prep_item(const Params& P, int l, int n, int hh, char* smem) {
;     ...
;       for (int j = 0; j < 4; ++j) { const int row = tabs - 3 + j, rr = row < 0 ? 0 : row;
;         pv[j][0] = *(const u32x4*)(proj + (size_t)rr * DINP + cb); pv[j][1] = *(const u32x4*)(proj + (size_t)rr * DINP + cb + 8);
;         const float* cw = P.gdn_conv + ((size_t)l * 4 + j) * 3072 + cb;
; #pragma unroll
;         for (int e4 = 0; e4 < 4; ++e4) wv[j][e4] = *(const f32x4*)(cw + 4 * e4); }
;       __builtin_amdgcn_sched_barrier(0);
; #pragma unroll
;       for (int j = 0; j < 4; ++j) { const float msk = (tabs - 3 + j) >= 0 ? 1.f : 0.f;
;         float xv[16]; unpack8(pv[j][0], xv); unpack8(pv[j][1], xv + 8);
; #pragma unroll
;         for (int e4 = 0; e4 < 4; ++e4) { const f32x4 wm = wv[j][e4] * msk; y[4 * e4] += wm.x * xv[4 * e4]; y[4 * e4 + 1] += wm.y * xv[4 * e4 + 1]; y[4 * e4 + 2] += wm.z * xv[4 * e4 + 2]; y[4 * e4 + 3] += wm.w * xv[4 * e4 + 3]; } }
; #pragma unroll
;       for (int e = 0; e < 16; ++e) y[e] = silu_f(y[e]);
	v_lshl_add_u64 v[10:11], v[2:3], 0, v[4:5]
	v_mad_u64_u32 v[2:3], s[2:3], v78, s81, v[56:57]
	v_lshl_add_u64 v[6:7], v[2:3], 0, v[14:15]
	global_load_dwordx4 v[2:5], v[6:7], off
	global_load_dwordx4 v[42:45], v[6:7], off offset:16
	v_mad_u64_u32 v[6:7], s[2:3], v77, s81, v[56:57]
	v_lshl_add_u64 v[112:113], v[10:11], 0, s[0:1]
	v_lshl_add_u64 v[12:13], v[6:7], 0, v[14:15]
	v_lshl_add_u64 v[10:11], v[10:11], 0, s[4:5]
	global_load_dwordx4 v[18:21], v[112:113], off
	global_load_dwordx4 v[46:49], v[112:113], off offset:16
	global_load_dwordx4 v[66:69], v[112:113], off offset:32
	global_load_dwordx4 v[22:25], v[112:113], off offset:48
	global_load_dwordx4 v[6:9], v[12:13], off
	global_load_dwordx4 v[70:73], v[12:13], off offset:16
	global_load_dwordx4 v[26:29], v[10:11], off
	global_load_dwordx4 v[84:87], v[10:11], off offset:16
	global_load_dwordx4 v[88:91], v[10:11], off offset:32
	global_load_dwordx4 v[30:33], v[10:11], off offset:48
	v_mad_u64_u32 v[10:11], s[2:3], v76, s81, v[56:57]
	v_lshl_add_u64 v[16:17], v[10:11], 0, v[14:15]
	v_add_co_u32_e32 v36, vcc, s10, v112
	global_load_dwordx4 v[10:13], v[16:17], off
	global_load_dwordx4 v[92:95], v[16:17], off offset:16
	v_lshl_add_u64 v[16:17], v[112:113], 0, s[12:13]
	v_addc_co_u32_e32 v37, vcc, 0, v113, vcc
	global_load_dwordx4 v[96:99], v[16:17], off offset:16
	global_load_dwordx4 v[100:103], v[16:17], off offset:32
	global_load_dwordx4 v[104:107], v[36:37], off
	s_nop 0
	global_load_dwordx4 v[36:39], v[16:17], off offset:48
	v_mad_u64_u32 v[16:17], s[2:3], v75, s81, v[56:57]
	v_add_co_u32_e32 v120, vcc, s18, v112
	v_lshl_add_u64 v[108:109], v[16:17], 0, v[14:15]
	v_lshl_add_u64 v[124:125], v[112:113], 0, s[14:15]
	v_addc_co_u32_e32 v121, vcc, 0, v113, vcc
	global_load_dwordx4 v[14:17], v[108:109], off
	s_nop 0
	global_load_dwordx4 v[108:111], v[108:109], off offset:16
	s_nop 0
	global_load_dwordx4 v[112:115], v[124:125], off offset:16
	global_load_dwordx4 v[116:119], v[124:125], off offset:32
	s_nop 0
	global_load_dwordx4 v[120:123], v[120:121], off
	s_nop 0
	global_load_dwordx4 v[124:127], v[124:125], off offset:48
	s_waitcnt vmcnt(0) lgkmcnt(0)
	v_pk_mul_f32 v[136:137], v[58:59], v[24:25] op_sel_hi:[0,1]
	v_pk_mul_f32 v[24:25], v[60:61], v[26:27] op_sel_hi:[0,1]
	v_pk_mul_f32 v[26:27], v[62:63], v[104:105] op_sel_hi:[0,1]
	v_pk_mul_f32 v[104:105], v[64:65], v[114:115] op_sel_hi:[0,1]
	v_lshlrev_b32_e32 v114, 16, v45
	v_and_b32_e32 v115, 0xffff0000, v45
	v_pk_mul_f32 v[130:131], v[62:63], v[36:37] op_sel_hi:[0,1]
	v_pk_mul_f32 v[132:133], v[60:61], v[32:33] op_sel_hi:[0,1]
	v_pk_mul_f32 v[36:37], v[62:63], v[106:107] op_sel_hi:[0,1]
	v_pk_mul_f32 v[106:107], v[64:65], v[112:113] op_sel_hi:[0,1]
	v_lshlrev_b32_e32 v112, 16, v73
	v_and_b32_e32 v113, 0xffff0000, v73
	v_pk_fma_f32 v[114:115], v[136:137], v[114:115], 0 op_sel_hi:[1,1,0]
	v_pk_mul_f32 v[128:129], v[62:63], v[38:39] op_sel_hi:[0,1]
	v_pk_mul_f32 v[134:135], v[60:61], v[30:31] op_sel_hi:[0,1]
	v_pk_mul_f32 v[30:31], v[58:59], v[20:21] op_sel_hi:[0,1]
	v_lshlrev_b32_e32 v20, 16, v95
	v_and_b32_e32 v21, 0xffff0000, v95
	v_pk_fma_f32 v[112:113], v[132:133], v[112:113], v[114:115]
	v_pk_mul_f32 v[126:127], v[64:65], v[126:127] op_sel_hi:[0,1]
	v_pk_mul_f32 v[138:139], v[58:59], v[22:23] op_sel_hi:[0,1]
	v_pk_mul_f32 v[22:23], v[58:59], v[18:19] op_sel_hi:[0,1]
	v_lshlrev_b32_e32 v18, 16, v111
	v_and_b32_e32 v19, 0xffff0000, v111
	v_pk_fma_f32 v[20:21], v[128:129], v[20:21], v[112:113]
	v_lshlrev_b32_e32 v114, 16, v110
	v_pk_fma_f32 v[18:19], v[126:127], v[18:19], v[20:21]
	v_and_b32_e32 v115, 0xffff0000, v110
	v_mul_f32_e32 v20, 0xbfb8aa3b, v19
	v_exp_f32_e32 v20, v20
	v_mul_f32_e32 v21, 0xbfb8aa3b, v18
	v_lshlrev_b32_e32 v110, 16, v94
	v_and_b32_e32 v111, 0xffff0000, v94
	v_lshlrev_b32_e32 v94, 16, v72
	v_and_b32_e32 v95, 0xffff0000, v72
	v_lshlrev_b32_e32 v72, 16, v44
	v_and_b32_e32 v73, 0xffff0000, v44
	v_exp_f32_e32 v41, v21
	v_pk_fma_f32 v[44:45], v[138:139], v[72:73], 0 op_sel_hi:[1,1,0]
	v_pk_mul_f32 v[124:125], v[64:65], v[124:125] op_sel_hi:[0,1]
	v_pk_fma_f32 v[44:45], v[134:135], v[94:95], v[44:45]
	v_add_f32_e32 v20, 1.0, v20
	v_pk_fma_f32 v[44:45], v[130:131], v[110:111], v[44:45]
	v_rcp_f32_e32 v21, v20
	v_pk_fma_f32 v[44:45], v[124:125], v[114:115], v[44:45]
	v_add_f32_e32 v20, 1.0, v41
	v_mul_f32_e32 v41, 0xbfb8aa3b, v44
	v_exp_f32_e32 v41, v41
	v_mul_f32_e32 v72, 0xbfb8aa3b, v45
	v_exp_f32_e32 v73, v72
	v_rcp_f32_e32 v20, v20
	v_add_f32_e32 v41, 1.0, v41
	v_rcp_f32_e32 v72, v41
	v_add_f32_e32 v41, 1.0, v73
	v_rcp_f32_e32 v73, v41
	v_pk_mul_f32 v[68:69], v[58:59], v[68:69] op_sel_hi:[0,1]
	v_pk_mul_f32 v[94:95], v[64:65], v[116:117] op_sel_hi:[0,1]
	v_lshlrev_b32_e32 v116, 16, v43
	v_and_b32_e32 v117, 0xffff0000, v43
	v_pk_mul_f32 v[90:91], v[60:61], v[90:91] op_sel_hi:[0,1]
	v_lshlrev_b32_e32 v114, 16, v71
	v_and_b32_e32 v115, 0xffff0000, v71
	v_pk_fma_f32 v[68:69], v[68:69], v[116:117], 0 op_sel_hi:[1,1,0]
	v_pk_mul_f32 v[102:103], v[62:63], v[102:103] op_sel_hi:[0,1]
	v_pk_mul_f32 v[18:19], v[18:19], v[20:21]
	v_pk_mul_f32 v[20:21], v[44:45], v[72:73]
	v_lshlrev_b32_e32 v72, 16, v93
	v_and_b32_e32 v73, 0xffff0000, v93
	v_pk_fma_f32 v[68:69], v[90:91], v[114:115], v[68:69]
	v_pk_mul_f32 v[112:113], v[64:65], v[118:119] op_sel_hi:[0,1]
	v_lshlrev_b32_e32 v44, 16, v109
	v_and_b32_e32 v45, 0xffff0000, v109
	v_pk_fma_f32 v[68:69], v[102:103], v[72:73], v[68:69]
	v_pk_mul_f32 v[66:67], v[58:59], v[66:67] op_sel_hi:[0,1]
	v_pk_fma_f32 v[44:45], v[112:113], v[44:45], v[68:69]
	v_lshlrev_b32_e32 v102, 16, v92
	v_mul_f32_e32 v41, 0xbfb8aa3b, v44
	v_exp_f32_e32 v41, v41
	v_mul_f32_e32 v43, 0xbfb8aa3b, v45
	v_exp_f32_e32 v43, v43
; DI float silu_f(float x) { return x * __builtin_amdgcn_rcpf(1.f + __expf(-x)); }
; DI void gdn_prep_item(const Params& P, int l, int n, int hh, char* smem) {
;     ...
;       for (int e = 0; e < 16; ++e) y[e] = silu_f(y[e]);
;       if (X < 2) { float ss = 0.f;
; #pragma unroll
;         for (int e = 0; e < 16; ++e) ss += y[e] * y[e];
;         ss += __shfl_xor(ss, 1); ss += __shfl_xor(ss, 2); ss += __shfl_xor(ss, 4);
;         const float rn = rsqrtf(ss + EPS) * (X == 0 ? 0.08838834764831845f : 1.f);
; #pragma unroll
;         for (int e = 0; e < 16; ++e) y[e] *= rn; }
	v_and_b32_e32 v103, 0xffff0000, v92
	v_add_f32_e32 v41, 1.0, v41
	v_lshlrev_b32_e32 v92, 16, v70
	v_and_b32_e32 v93, 0xffff0000, v70
	v_lshlrev_b32_e32 v70, 16, v42
	v_and_b32_e32 v71, 0xffff0000, v42
	v_pk_mul_f32 v[88:89], v[60:61], v[88:89] op_sel_hi:[0,1]
	v_rcp_f32_e32 v72, v41
	v_add_f32_e32 v41, 1.0, v43
	v_pk_fma_f32 v[42:43], v[66:67], v[70:71], 0 op_sel_hi:[1,1,0]
	v_pk_mul_f32 v[100:101], v[62:63], v[100:101] op_sel_hi:[0,1]
	v_rcp_f32_e32 v73, v41
	v_pk_fma_f32 v[42:43], v[88:89], v[92:93], v[42:43]
	v_lshlrev_b32_e32 v90, 16, v108
	v_and_b32_e32 v91, 0xffff0000, v108
	v_pk_fma_f32 v[42:43], v[100:101], v[102:103], v[42:43]
	v_pk_mul_f32 v[48:49], v[58:59], v[48:49] op_sel_hi:[0,1]
	v_pk_fma_f32 v[42:43], v[94:95], v[90:91], v[42:43]
	v_lshlrev_b32_e32 v90, 16, v5
	v_and_b32_e32 v91, 0xffff0000, v5
	v_pk_mul_f32 v[86:87], v[60:61], v[86:87] op_sel_hi:[0,1]
	v_lshlrev_b32_e32 v88, 16, v9
	v_and_b32_e32 v89, 0xffff0000, v9
	v_pk_fma_f32 v[48:49], v[48:49], v[90:91], 0 op_sel_hi:[1,1,0]
	v_pk_mul_f32 v[98:99], v[62:63], v[98:99] op_sel_hi:[0,1]
	v_pk_mul_f32 v[44:45], v[44:45], v[72:73]
	v_lshlrev_b32_e32 v72, 16, v13
	v_and_b32_e32 v73, 0xffff0000, v13
	v_pk_fma_f32 v[48:49], v[86:87], v[88:89], v[48:49]
	v_lshlrev_b32_e32 v70, 16, v17
	v_and_b32_e32 v71, 0xffff0000, v17
	v_pk_fma_f32 v[48:49], v[98:99], v[72:73], v[48:49]
	v_pk_mul_f32 v[46:47], v[58:59], v[46:47] op_sel_hi:[0,1]
	v_pk_fma_f32 v[48:49], v[104:105], v[70:71], v[48:49]
	v_and_b32_e32 v17, 0xffff0000, v12
	v_mul_f32_e32 v5, 0xbfb8aa3b, v48
	v_exp_f32_e32 v5, v5
	v_mul_f32_e32 v9, 0xbfb8aa3b, v49
	v_exp_f32_e32 v9, v9
	v_and_b32_e32 v13, 0xffff0000, v8
	v_add_f32_e32 v5, 1.0, v5
	v_rcp_f32_e32 v70, v5
	v_add_f32_e32 v5, 1.0, v9
	v_rcp_f32_e32 v71, v5
	v_and_b32_e32 v9, 0xffff0000, v4
	v_pk_mul_f32 v[84:85], v[60:61], v[84:85] op_sel_hi:[0,1]
	v_pk_mul_f32 v[96:97], v[62:63], v[96:97] op_sel_hi:[0,1]
	v_pk_mul_f32 v[48:49], v[48:49], v[70:71]
	v_lshlrev_b32_e32 v70, 16, v16
	v_and_b32_e32 v71, 0xffff0000, v16
	v_lshlrev_b32_e32 v16, 16, v12
	v_lshlrev_b32_e32 v12, 16, v8
	v_lshlrev_b32_e32 v8, 16, v4
	v_pk_fma_f32 v[4:5], v[46:47], v[8:9], 0 op_sel_hi:[1,1,0]
	v_pk_mul_f32 v[32:33], v[60:61], v[28:29] op_sel_hi:[0,1]
	v_pk_fma_f32 v[4:5], v[84:85], v[12:13], v[4:5]
	v_lshlrev_b32_e32 v84, 16, v3
	v_pk_fma_f32 v[4:5], v[96:97], v[16:17], v[4:5]
	v_and_b32_e32 v85, 0xffff0000, v3
	v_pk_fma_f32 v[4:5], v[106:107], v[70:71], v[4:5]
	v_lshlrev_b32_e32 v70, 16, v7
	v_mul_f32_e32 v8, 0xbfb8aa3b, v4
	v_exp_f32_e32 v12, v8
	v_mul_f32_e32 v8, 0xbfb8aa3b, v5
	v_exp_f32_e32 v13, v8
	v_and_b32_e32 v71, 0xffff0000, v7
	v_pk_fma_f32 v[30:31], v[30:31], v[84:85], 0 op_sel_hi:[1,1,0]
	v_lshlrev_b32_e32 v46, 16, v11
	v_and_b32_e32 v47, 0xffff0000, v11
	v_pk_fma_f32 v[30:31], v[32:33], v[70:71], v[30:31]
	v_pk_mul_f32 v[38:39], v[64:65], v[122:123] op_sel_hi:[0,1]
	v_lshlrev_b32_e32 v16, 16, v15
	v_and_b32_e32 v17, 0xffff0000, v15
	v_pk_fma_f32 v[30:31], v[36:37], v[46:47], v[30:31]
	v_add_f32_e32 v12, 1.0, v12
	v_pk_fma_f32 v[16:17], v[38:39], v[16:17], v[30:31]
	v_add_f32_e32 v13, 1.0, v13
	v_mul_f32_e32 v3, 0xbfb8aa3b, v16
	v_mul_f32_e32 v7, 0xbfb8aa3b, v17
	v_rcp_f32_e32 v12, v12
	v_rcp_f32_e32 v13, v13
	v_exp_f32_e32 v3, v3
	v_exp_f32_e32 v7, v7
	v_lshlrev_b32_e32 v30, 16, v14
	v_pk_mul_f32 v[12:13], v[4:5], v[12:13]
	v_add_f32_e32 v3, 1.0, v3
	v_add_f32_e32 v5, 1.0, v7
	v_and_b32_e32 v31, 0xffff0000, v14
	v_lshlrev_b32_e32 v14, 16, v10
	v_and_b32_e32 v15, 0xffff0000, v10
	v_lshlrev_b32_e32 v10, 16, v6
	v_and_b32_e32 v11, 0xffff0000, v6
	v_lshlrev_b32_e32 v6, 16, v2
	v_and_b32_e32 v7, 0xffff0000, v2
	v_rcp_f32_e32 v4, v3
	v_pk_fma_f32 v[2:3], v[22:23], v[6:7], 0 op_sel_hi:[1,1,0]
	v_pk_mul_f32 v[28:29], v[64:65], v[120:121] op_sel_hi:[0,1]
	v_pk_fma_f32 v[2:3], v[24:25], v[10:11], v[2:3]
	v_mul_f32_e32 v41, 0xbfb8aa3b, v42
	v_pk_fma_f32 v[2:3], v[26:27], v[14:15], v[2:3]
	v_exp_f32_e32 v41, v41
	v_pk_fma_f32 v[2:3], v[28:29], v[30:31], v[2:3]
	v_mul_f32_e32 v66, 0xbfb8aa3b, v43
	v_mul_f32_e32 v6, 0xbfb8aa3b, v2
	v_mul_f32_e32 v7, 0xbfb8aa3b, v3
	v_exp_f32_e32 v6, v6
	v_exp_f32_e32 v7, v7
	v_rcp_f32_e32 v5, v5
	v_exp_f32_e32 v67, v66
	v_add_f32_e32 v6, 1.0, v6
	v_add_f32_e32 v7, 1.0, v7
	v_rcp_f32_e32 v6, v6
	v_rcp_f32_e32 v7, v7
	v_add_f32_e32 v41, 1.0, v41
	v_pk_mul_f32 v[4:5], v[16:17], v[4:5]
	v_rcp_f32_e32 v66, v41
	v_pk_mul_f32 v[2:3], v[2:3], v[6:7]
	v_add_f32_e32 v41, 1.0, v67
	v_pk_mul_f32 v[6:7], v[2:3], v[2:3]
	v_pk_mul_f32 v[14:15], v[4:5], v[4:5]
	v_add_f32_e32 v6, v6, v7
	v_rcp_f32_e32 v67, v41
	v_add_f32_e32 v6, v14, v6
	v_pk_mul_f32 v[10:11], v[12:13], v[12:13]
	v_add_f32_e32 v6, v15, v6
	global_load_dwordx2 v[26:27], v1, s[40:41] offset:1096
	v_add_f32_e32 v6, v10, v6
	v_pk_mul_f32 v[8:9], v[48:49], v[48:49]
	v_add_f32_e32 v6, v11, v6
	v_pk_mul_f32 v[42:43], v[42:43], v[66:67]
	v_add_f32_e32 v6, v8, v6
	v_pk_mul_f32 v[66:67], v[42:43], v[42:43]
	v_add_f32_e32 v6, v9, v6
	v_add_f32_e32 v6, v66, v6
	v_pk_mul_f32 v[72:73], v[44:45], v[44:45]
	v_add_f32_e32 v6, v67, v6
	v_add_f32_e32 v6, v72, v6
	v_pk_mul_f32 v[68:69], v[20:21], v[20:21]
	v_add_f32_e32 v6, v73, v6
	v_add_f32_e32 v6, v68, v6
	v_pk_mul_f32 v[110:111], v[18:19], v[18:19]
	v_add_f32_e32 v6, v69, v6
	v_add_f32_e32 v6, v110, v6
	v_add_f32_e32 v6, v111, v6
	s_nop 1
	v_lshlrev_b32_e32 v84, 10, v79
	s_mov_b64 s[2:3], 0x212e8000
	s_waitcnt lgkmcnt(0)
	v_add_f32_dpp v6, v6, v6 quad_perm:[1,0,3,2] row_mask:0xf bank_mask:0xf
	s_nop 1
	s_waitcnt lgkmcnt(0)
	v_add_f32_dpp v6, v6, v6 quad_perm:[2,3,0,1] row_mask:0xf bank_mask:0xf
	s_nop 1
	v_mov_b32_dpp v7, v6 row_ror:4 row_mask:0xf bank_mask:0xa
	v_mov_b32_dpp v7, v6 row_ror:12 row_mask:0xf bank_mask:0x5
	s_waitcnt lgkmcnt(0)
; DI unsigned pack2(float lo, float hi) { f32x2 v = {lo, hi}; bf2_t b = __builtin_convertvector(v, bf2_t); return __builtin_bit_cast(unsigned, b); }
; DI bf16_t f2bf(float x) { return (bf16_t)(pack2(x, 0.f) & 0xffffu); }
; DI void gdn_prep_item(const Params& P, int l, int n, int hh, char* smem) {
;     ...
;       for (int j = 0; j < 4; ++j) { const int row = tabs - 3 + j, rr = row < 0 ? 0 : row;
;         pv[j][0] = *(const u32x4*)(proj + (size_t)rr * DINP + cb); pv[j][1] = *(const u32x4*)(proj + (size_t)rr * DINP + cb + 8);
;         const float* cw = P.gdn_conv + ((size_t)l * 4 + j) * 3072 + cb;
; #pragma unroll
;         for (int e4 = 0; e4 < 4; ++e4) wv[j][e4] = *(const f32x4*)(cw + 4 * e4); }
;     ...
;         const float rn = rsqrtf(ss + EPS) * (X == 0 ? 0.08838834764831845f : 1.f);
; #pragma unroll
;         for (int e = 0; e < 16; ++e) y[e] *= rn; }
;       if (X == 0) {
;         u32x4 p0 = {pack2(y[0], y[1]), pack2(y[2], y[3]), pack2(y[4], y[5]), pack2(y[6], y[7])}, p1 = {pack2(y[8], y[9]), pack2(y[10], y[11]), pack2(y[12], y[13]), pack2(y[14], y[15])};
;         *(u32x4*)(qb16 + t * 272 + part * 32) = p0; *(u32x4*)(qb16 + t * 272 + part * 32 + 16) = p1;
; #pragma unroll
;         for (int b = 0; b < 4; ++b) { u32x2 pk = {pack2(y[4 * b] * egct, y[4 * b + 1] * egct), pack2(y[4 * b + 2] * egct, y[4 * b + 3] * egct)};
;           *(u32x2*)(Qd + t * 128 + 32 * (part >> 1) + 8 * b + 4 * (part & 1)) = pk; }
;       } else if (X == 1) {
;         u32x4 p0 = {pack2(y[0], y[1]), pack2(y[2], y[3]), pack2(y[4], y[5]), pack2(y[6], y[7])}, p1 = {pack2(y[8], y[9]), pack2(y[10], y[11]), pack2(y[12], y[13]), pack2(y[14], y[15])};
;         *(u32x4*)(kb16 + t * 272 + part * 32) = p0; *(u32x4*)(kb16 + t * 272 + part * 32 + 16) = p1;
; #pragma unroll
;         for (int e4 = 0; e4 < 4; ++e4) { f32x4 v = {y[4 * e4], y[4 * e4 + 1], y[4 * e4 + 2], y[4 * e4 + 3]}; *(f32x4*)(kf + t * 128 + part * 16 + 4 * e4) = v; }
; #pragma unroll
;         for (int e = 0; e < 16; ++e) Kt[(part * 16 + e) * 64 + pjt] = f2bf(y[e] * ktl);
	v_add_f32_e32 v6, v6, v7
	v_add_f32_e32 v6, 0x358637bd, v6
	v_mul_f32_e32 v7, 0x4b800000, v6
	v_cmp_gt_f32_e32 vcc, s84, v6
	s_nop 1
	v_cndmask_b32_e32 v6, v6, v7, vcc
	v_rsq_f32_e32 v6, v6
	s_nop 0
	v_mul_f32_e32 v7, 0x45800000, v6
	v_cndmask_b32_e32 v16, v6, v7, vcc
	v_pk_mul_f32 v[2:3], v[2:3], v[16:17] op_sel_hi:[1,0]
	v_pk_mul_f32 v[4:5], v[4:5], v[16:17] op_sel_hi:[1,0]
	v_pk_mul_f32 v[6:7], v[12:13], v[16:17] op_sel_hi:[1,0]
	v_pk_mul_f32 v[8:9], v[48:49], v[16:17] op_sel_hi:[1,0]
	v_pk_mul_f32 v[10:11], v[42:43], v[16:17] op_sel_hi:[1,0]
	v_pk_mul_f32 v[12:13], v[44:45], v[16:17] op_sel_hi:[1,0]
	v_pk_mul_f32 v[14:15], v[20:21], v[16:17] op_sel_hi:[1,0]
	v_pk_mul_f32 v[16:17], v[18:19], v[16:17] op_sel_hi:[1,0]
	v_cvt_pk_bf16_f32 v18, v2, v3
	v_cvt_pk_bf16_f32 v19, v4, v5
	v_cvt_pk_bf16_f32 v20, v6, v7
	v_cvt_pk_bf16_f32 v21, v8, v9
	v_cvt_pk_bf16_f32 v22, v10, v11
	v_cvt_pk_bf16_f32 v23, v12, v13
	v_cvt_pk_bf16_f32 v24, v14, v15
	v_cvt_pk_bf16_f32 v25, v16, v17
	ds_write_b128 v34, v[18:21]
	ds_write_b128 v34, v[22:25] offset:16
	ds_write_b128 v80, v[2:5] offset:34816
	ds_write_b128 v80, v[6:9] offset:34832
	ds_write_b128 v80, v[10:13] offset:34848
	ds_write_b128 v80, v[14:17] offset:34864
	v_add_u32_e32 v18, v35, v84
	v_ashrrev_i32_e32 v19, 31, v18
	v_lshl_add_u64 v[18:19], v[18:19], 1, v[54:55]
	v_lshl_add_u64 v[20:21], v[18:19], 0, s[2:3]
	s_mov_b32 s2, 0x212e8000
	v_mul_f32_e32 v2, v40, v2
	v_add_co_u32_e32 v18, vcc, s2, v18
	v_cvt_pk_bf16_f32 v2, v2, s0
	s_nop 0
	v_addc_co_u32_e32 v19, vcc, 0, v19, vcc
	global_store_short v[18:19], v2, off
	v_mul_f32_e32 v2, v40, v3
	v_cvt_pk_bf16_f32 v2, v2, s0
	global_store_short v[20:21], v2, off offset:128
	v_mul_f32_e32 v2, v40, v4
	v_cvt_pk_bf16_f32 v2, v2, s0
	global_store_short v[20:21], v2, off offset:256
	v_mul_f32_e32 v2, v40, v5
	v_cvt_pk_bf16_f32 v2, v2, s0
	global_store_short v[20:21], v2, off offset:384
	v_mul_f32_e32 v2, v40, v6
	v_cvt_pk_bf16_f32 v2, v2, s0
	global_store_short v[20:21], v2, off offset:512
	v_mul_f32_e32 v2, v40, v7
	v_cvt_pk_bf16_f32 v2, v2, s0
	global_store_short v[20:21], v2, off offset:640
	v_mul_f32_e32 v2, v40, v8
	v_cvt_pk_bf16_f32 v2, v2, s0
	global_store_short v[20:21], v2, off offset:768
	v_mul_f32_e32 v2, v40, v9
	v_cvt_pk_bf16_f32 v2, v2, s0
	global_store_short v[20:21], v2, off offset:896
	v_mul_f32_e32 v2, v40, v10
	v_cvt_pk_bf16_f32 v2, v2, s0
	global_store_short v[20:21], v2, off offset:1024
	v_mul_f32_e32 v2, v40, v11
	v_cvt_pk_bf16_f32 v2, v2, s0
	global_store_short v[20:21], v2, off offset:1152
	v_mul_f32_e32 v2, v40, v12
	v_cvt_pk_bf16_f32 v2, v2, s0
	global_store_short v[20:21], v2, off offset:1280
	v_mul_f32_e32 v2, v40, v13
	v_cvt_pk_bf16_f32 v2, v2, s0
	global_store_short v[20:21], v2, off offset:1408
	v_mul_f32_e32 v2, v40, v14
	v_cvt_pk_bf16_f32 v2, v2, s0
	global_store_short v[20:21], v2, off offset:1536
	v_mul_f32_e32 v2, v40, v15
	v_cvt_pk_bf16_f32 v2, v2, s0
	global_store_short v[20:21], v2, off offset:1664
	v_mul_f32_e32 v2, v40, v16
	v_cvt_pk_bf16_f32 v2, v2, s0
	global_store_short v[20:21], v2, off offset:1792
	v_mul_f32_e32 v2, v40, v17
	v_cvt_pk_bf16_f32 v2, v2, s0
	v_or_b32_e32 v4, 0x800, v74
	global_store_short v[20:21], v2, off offset:1920
	v_lshlrev_b32_e32 v2, 1, v4
	v_mov_b32_e32 v3, v1
	v_lshl_add_u64 v[14:15], v[56:57], 0, v[2:3]
	v_lshlrev_b32_e32 v2, 2, v4
	s_waitcnt vmcnt(0)
	v_lshl_add_u64 v[10:11], v[26:27], 0, v[2:3]
	v_lshl_add_u64 v[30:31], v[10:11], 0, s[0:1]
	v_add_co_u32_e32 v26, vcc, s10, v30
	v_mad_u64_u32 v[6:7], s[2:3], v78, s81, v[14:15]
	v_mad_u64_u32 v[12:13], s[2:3], v77, s81, v[14:15]
	v_lshl_add_u64 v[10:11], v[10:11], 0, s[4:5]
	v_mad_u64_u32 v[16:17], s[2:3], v76, s81, v[14:15]
	v_addc_co_u32_e32 v27, vcc, 0, v31, vcc
	global_load_dwordx4 v[2:5], v[6:7], off
	global_load_dwordx4 v[78:81], v[6:7], off offset:16
	global_load_dwordx4 v[18:21], v[30:31], off
	global_load_dwordx4 v[34:37], v[30:31], off offset:16
	global_load_dwordx4 v[86:89], v[30:31], off offset:32
	global_load_dwordx4 v[66:69], v[30:31], off offset:48
	s_nop 0
	global_load_dwordx4 v[6:9], v[12:13], off
	global_load_dwordx4 v[90:93], v[12:13], off offset:16
	global_load_dwordx4 v[22:25], v[10:11], off
	global_load_dwordx4 v[38:41], v[10:11], off offset:16
	global_load_dwordx4 v[94:97], v[10:11], off offset:32
	global_load_dwordx4 v[70:73], v[10:11], off offset:48
	s_nop 0
	global_load_dwordx4 v[10:13], v[16:17], off
	global_load_dwordx4 v[98:101], v[16:17], off offset:16
	v_lshl_add_u64 v[16:17], v[30:31], 0, s[12:13]
	v_lshl_add_u64 v[114:115], v[30:31], 0, s[14:15]
	v_add_co_u32_e32 v30, vcc, s18, v30
	v_mad_u64_u32 v[32:33], s[2:3], v75, s81, v[14:15]
	s_nop 0
	v_addc_co_u32_e32 v31, vcc, 0, v31, vcc
	global_load_dwordx4 v[42:45], v[16:17], off offset:16
	global_load_dwordx4 v[102:105], v[16:17], off offset:32
	s_nop 0
	global_load_dwordx4 v[26:29], v[26:27], off
	s_nop 0
	global_load_dwordx4 v[106:109], v[16:17], off offset:48
	s_nop 0
	global_load_dwordx4 v[14:17], v[32:33], off
	global_load_dwordx4 v[110:113], v[32:33], off offset:16
	global_load_dwordx4 v[46:49], v[114:115], off offset:16
	global_load_dwordx4 v[74:77], v[114:115], off offset:32
	s_nop 0
	global_load_dwordx4 v[30:33], v[30:31], off
	s_nop 0
	global_load_dwordx4 v[114:117], v[114:115], off offset:48
	s_waitcnt vmcnt(0) lgkmcnt(0)
; DI void unpack8(const u32x4& v, float* f) { f[0] = bflo(v.x); f[1] = bfhi(v.x); f[2] = bflo(v.y); f[3] = bfhi(v.y); f[4] = bflo(v.z); f[5] = bfhi(v.z); f[6] = bflo(v.w); f[7] = bfhi(v.w); }
; DI float silu_f(float x) { return x * __builtin_amdgcn_rcpf(1.f + __expf(-x)); }
; DI void gdn_prep_item(const Params& P, int l, int n, int hh, char* smem) {
;     ...
;       for (int j = 0; j < 4; ++j) { const int row = tabs - 3 + j, rr = row < 0 ? 0 : row;
;         pv[j][0] = *(const u32x4*)(proj + (size_t)rr * DINP + cb); pv[j][1] = *(const u32x4*)(proj + (size_t)rr * DINP + cb + 8);
;         const float* cw = P.gdn_conv + ((size_t)l * 4 + j) * 3072 + cb;
; #pragma unroll
;         for (int e4 = 0; e4 < 4; ++e4) wv[j][e4] = *(const f32x4*)(cw + 4 * e4); }
;       __builtin_amdgcn_sched_barrier(0);
; #pragma unroll
;       for (int j = 0; j < 4; ++j) { const float msk = (tabs - 3 + j) >= 0 ? 1.f : 0.f;
;         float xv[16]; unpack8(pv[j][0], xv); unpack8(pv[j][1], xv + 8);
; #pragma unroll
;         for (int e4 = 0; e4 < 4; ++e4) { const f32x4 wm = wv[j][e4] * msk; y[4 * e4] += wm.x * xv[4 * e4]; y[4 * e4 + 1] += wm.y * xv[4 * e4 + 1]; y[4 * e4 + 2] += wm.z * xv[4 * e4 + 2]; y[4 * e4 + 3] += wm.w * xv[4 * e4 + 3]; } }
; #pragma unroll
;       for (int e = 0; e < 16; ++e) y[e] = silu_f(y[e]);
	v_pk_mul_f32 v[68:69], v[58:59], v[68:69] op_sel_hi:[0,1]
	v_lshlrev_b32_e32 v124, 16, v81
	v_and_b32_e32 v125, 0xffff0000, v81
	v_pk_mul_f32 v[72:73], v[60:61], v[72:73] op_sel_hi:[0,1]
	v_lshlrev_b32_e32 v122, 16, v93
	v_and_b32_e32 v123, 0xffff0000, v93
	v_pk_fma_f32 v[68:69], v[68:69], v[124:125], 0 op_sel_hi:[1,1,0]
	v_pk_mul_f32 v[118:119], v[58:59], v[66:67] op_sel_hi:[0,1]
	v_pk_fma_f32 v[68:69], v[72:73], v[122:123], v[68:69]
	v_lshlrev_b32_e32 v72, 16, v80
	v_and_b32_e32 v73, 0xffff0000, v80
	v_pk_mul_f32 v[70:71], v[60:61], v[70:71] op_sel_hi:[0,1]
	v_pk_fma_f32 v[72:73], v[118:119], v[72:73], 0 op_sel_hi:[1,1,0]
	v_lshlrev_b32_e32 v80, 16, v92
	v_and_b32_e32 v81, 0xffff0000, v92
	v_pk_mul_f32 v[106:107], v[62:63], v[106:107] op_sel_hi:[0,1]
	v_pk_fma_f32 v[70:71], v[70:71], v[80:81], v[72:73]
	v_lshlrev_b32_e32 v72, 16, v100
	v_and_b32_e32 v73, 0xffff0000, v100
	v_pk_fma_f32 v[70:71], v[106:107], v[72:73], v[70:71]
	v_pk_mul_f32 v[88:89], v[58:59], v[88:89] op_sel_hi:[0,1]
	v_lshlrev_b32_e32 v106, 16, v79
	v_and_b32_e32 v107, 0xffff0000, v79
	v_pk_mul_f32 v[80:81], v[64:65], v[74:75] op_sel_hi:[0,1]
	v_pk_mul_f32 v[74:75], v[62:63], v[104:105] op_sel_hi:[0,1]
	v_pk_mul_f32 v[96:97], v[60:61], v[96:97] op_sel_hi:[0,1]
	v_lshlrev_b32_e32 v104, 16, v91
	v_and_b32_e32 v105, 0xffff0000, v91
	v_pk_fma_f32 v[88:89], v[88:89], v[106:107], 0 op_sel_hi:[1,1,0]
	v_pk_mul_f32 v[92:93], v[62:63], v[102:103] op_sel_hi:[0,1]
	v_lshlrev_b32_e32 v102, 16, v99
	v_and_b32_e32 v103, 0xffff0000, v99
	v_pk_fma_f32 v[88:89], v[96:97], v[104:105], v[88:89]
	v_pk_mul_f32 v[86:87], v[58:59], v[86:87] op_sel_hi:[0,1]
	v_pk_fma_f32 v[74:75], v[74:75], v[102:103], v[88:89]
	v_lshlrev_b32_e32 v88, 16, v78
	v_and_b32_e32 v89, 0xffff0000, v78
	v_pk_mul_f32 v[94:95], v[60:61], v[94:95] op_sel_hi:[0,1]
	v_pk_fma_f32 v[78:79], v[86:87], v[88:89], 0 op_sel_hi:[1,1,0]
	v_lshlrev_b32_e32 v86, 16, v90
	v_and_b32_e32 v87, 0xffff0000, v90
	v_pk_fma_f32 v[78:79], v[94:95], v[86:87], v[78:79]
	v_lshlrev_b32_e32 v86, 16, v98
	v_and_b32_e32 v87, 0xffff0000, v98
	v_pk_fma_f32 v[78:79], v[92:93], v[86:87], v[78:79]
	v_pk_mul_f32 v[36:37], v[58:59], v[36:37] op_sel_hi:[0,1]
	v_lshlrev_b32_e32 v92, 16, v5
	v_and_b32_e32 v93, 0xffff0000, v5
	v_pk_mul_f32 v[40:41], v[60:61], v[40:41] op_sel_hi:[0,1]
	v_lshlrev_b32_e32 v90, 16, v9
	v_and_b32_e32 v91, 0xffff0000, v9
	v_pk_fma_f32 v[36:37], v[36:37], v[92:93], 0 op_sel_hi:[1,1,0]
	v_lshlrev_b32_e32 v86, 16, v110
	v_and_b32_e32 v87, 0xffff0000, v110
	v_pk_mul_f32 v[44:45], v[62:63], v[44:45] op_sel_hi:[0,1]
	v_lshlrev_b32_e32 v88, 16, v13
	v_and_b32_e32 v89, 0xffff0000, v13
	v_pk_fma_f32 v[36:37], v[40:41], v[90:91], v[36:37]
	v_pk_fma_f32 v[78:79], v[80:81], v[86:87], v[78:79]
	v_pk_mul_f32 v[48:49], v[64:65], v[48:49] op_sel_hi:[0,1]
	v_lshlrev_b32_e32 v86, 16, v17
	v_and_b32_e32 v87, 0xffff0000, v17
	v_pk_fma_f32 v[36:37], v[44:45], v[88:89], v[36:37]
	v_pk_mul_f32 v[34:35], v[58:59], v[34:35] op_sel_hi:[0,1]
	v_pk_fma_f32 v[36:37], v[48:49], v[86:87], v[36:37]
	v_lshlrev_b32_e32 v44, 16, v4
	v_mul_f32_e32 v5, 0xbfb8aa3b, v37
	v_exp_f32_e32 v5, v5
	v_and_b32_e32 v45, 0xffff0000, v4
	v_pk_mul_f32 v[38:39], v[60:61], v[38:39] op_sel_hi:[0,1]
	v_pk_mul_f32 v[42:43], v[62:63], v[42:43] op_sel_hi:[0,1]
	v_add_f32_e32 v5, 1.0, v5
	v_rcp_f32_e32 v41, v5
	v_mul_f32_e32 v5, 0xbfb8aa3b, v36
	v_exp_f32_e32 v5, v5
	v_and_b32_e32 v9, 0xffff0000, v12
	v_pk_mul_f32 v[46:47], v[64:65], v[46:47] op_sel_hi:[0,1]
	v_pk_mul_f32 v[20:21], v[58:59], v[20:21] op_sel_hi:[0,1]
	v_add_f32_e32 v5, 1.0, v5
	v_rcp_f32_e32 v40, v5
	v_pk_fma_f32 v[4:5], v[34:35], v[44:45], 0 op_sel_hi:[1,1,0]
	v_lshlrev_b32_e32 v34, 16, v8
	v_and_b32_e32 v35, 0xffff0000, v8
	v_pk_fma_f32 v[4:5], v[38:39], v[34:35], v[4:5]
	v_lshlrev_b32_e32 v8, 16, v12
	v_pk_fma_f32 v[4:5], v[42:43], v[8:9], v[4:5]
	v_lshlrev_b32_e32 v8, 16, v16
	v_and_b32_e32 v9, 0xffff0000, v16
	v_pk_fma_f32 v[8:9], v[46:47], v[8:9], v[4:5]
	v_lshlrev_b32_e32 v38, 16, v3
	v_mul_f32_e32 v4, 0xbfb8aa3b, v9
	v_exp_f32_e32 v4, v4
	v_and_b32_e32 v39, 0xffff0000, v3
	v_pk_mul_f32 v[24:25], v[60:61], v[24:25] op_sel_hi:[0,1]
	v_lshlrev_b32_e32 v34, 16, v7
	v_add_f32_e32 v4, 1.0, v4
	v_rcp_f32_e32 v13, v4
	v_mul_f32_e32 v4, 0xbfb8aa3b, v8
	v_exp_f32_e32 v4, v4
	v_and_b32_e32 v35, 0xffff0000, v7
	v_pk_fma_f32 v[20:21], v[20:21], v[38:39], 0 op_sel_hi:[1,1,0]
	v_pk_mul_f32 v[28:29], v[62:63], v[28:29] op_sel_hi:[0,1]
	v_add_f32_e32 v4, 1.0, v4
	v_rcp_f32_e32 v12, v4
	v_pk_mul_f32 v[4:5], v[64:65], v[32:33] op_sel_hi:[0,1]
	v_lshlrev_b32_e32 v32, 16, v11
	v_and_b32_e32 v33, 0xffff0000, v11
	v_pk_fma_f32 v[20:21], v[24:25], v[34:35], v[20:21]
	v_pk_mul_f32 v[16:17], v[64:65], v[30:31] op_sel_hi:[0,1]
	v_lshlrev_b32_e32 v30, 16, v15
	v_and_b32_e32 v31, 0xffff0000, v15
	v_pk_fma_f32 v[20:21], v[28:29], v[32:33], v[20:21]
	v_pk_mul_f32 v[18:19], v[58:59], v[18:19] op_sel_hi:[0,1]
	v_pk_fma_f32 v[4:5], v[4:5], v[30:31], v[20:21]
	v_lshlrev_b32_e32 v24, 16, v2
	v_mul_f32_e32 v3, 0xbfb8aa3b, v5
	v_exp_f32_e32 v3, v3
	v_and_b32_e32 v25, 0xffff0000, v2
	v_pk_mul_f32 v[22:23], v[60:61], v[22:23] op_sel_hi:[0,1]
	v_pk_mul_f32 v[26:27], v[62:63], v[26:27] op_sel_hi:[0,1]
	v_add_f32_e32 v3, 1.0, v3
	v_rcp_f32_e32 v21, v3
	v_mul_f32_e32 v3, 0xbfb8aa3b, v4
	v_exp_f32_e32 v3, v3
	v_and_b32_e32 v7, 0xffff0000, v10
	v_pk_mul_f32 v[108:109], v[62:63], v[108:109] op_sel_hi:[0,1]
	v_lshlrev_b32_e32 v120, 16, v101
	v_add_f32_e32 v3, 1.0, v3
	v_rcp_f32_e32 v20, v3
	v_pk_fma_f32 v[2:3], v[18:19], v[24:25], 0 op_sel_hi:[1,1,0]
	v_lshlrev_b32_e32 v18, 16, v6
	v_and_b32_e32 v19, 0xffff0000, v6
	v_pk_fma_f32 v[2:3], v[22:23], v[18:19], v[2:3]
; DI bf16_t f2bf(float x) { return (bf16_t)(pack2(x, 0.f) & 0xffffu); }
; DI void gdn_prep_item(const Params& P, int l, int n, int hh, char* smem) {
;     ...
;         for (int e4 = 0; e4 < 4; ++e4) { const f32x4 wm = wv[j][e4] * msk; y[4 * e4] += wm.x * xv[4 * e4]; y[4 * e4 + 1] += wm.y * xv[4 * e4 + 1]; y[4 * e4 + 2] += wm.z * xv[4 * e4 + 2]; y[4 * e4 + 3] += wm.w * xv[4 * e4 + 3]; } }
; #pragma unroll
;       for (int e = 0; e < 16; ++e) y[e] = silu_f(y[e]);
;       if (X < 2) { float ss = 0.f;
; #pragma unroll
;         for (int e = 0; e < 16; ++e) ss += y[e] * y[e];
;         ss += __shfl_xor(ss, 1); ss += __shfl_xor(ss, 2); ss += __shfl_xor(ss, 4);
;         const float rn = rsqrtf(ss + EPS) * (X == 0 ? 0.08838834764831845f : 1.f);
; #pragma unroll
;         for (int e = 0; e < 16; ++e) y[e] *= rn; }
;       if (X == 0) {
;         u32x4 p0 = {pack2(y[0], y[1]), pack2(y[2], y[3]), pack2(y[4], y[5]), pack2(y[6], y[7])}, p1 = {pack2(y[8], y[9]), pack2(y[10], y[11]), pack2(y[12], y[13]), pack2(y[14], y[15])};
;         *(u32x4*)(qb16 + t * 272 + part * 32) = p0; *(u32x4*)(qb16 + t * 272 + part * 32 + 16) = p1;
; #pragma unroll
;         for (int b = 0; b < 4; ++b) { u32x2 pk = {pack2(y[4 * b] * egct, y[4 * b + 1] * egct), pack2(y[4 * b + 2] * egct, y[4 * b + 3] * egct)};
;           *(u32x2*)(Qd + t * 128 + 32 * (part >> 1) + 8 * b + 4 * (part & 1)) = pk; }
;       } else if (X == 1) {
;         u32x4 p0 = {pack2(y[0], y[1]), pack2(y[2], y[3]), pack2(y[4], y[5]), pack2(y[6], y[7])}, p1 = {pack2(y[8], y[9]), pack2(y[10], y[11]), pack2(y[12], y[13]), pack2(y[14], y[15])};
;         *(u32x4*)(kb16 + t * 272 + part * 32) = p0; *(u32x4*)(kb16 + t * 272 + part * 32 + 16) = p1;
; #pragma unroll
;         for (int e4 = 0; e4 < 4; ++e4) { f32x4 v = {y[4 * e4], y[4 * e4 + 1], y[4 * e4 + 2], y[4 * e4 + 3]}; *(f32x4*)(kf + t * 128 + part * 16 + 4 * e4) = v; }
; #pragma unroll
;         for (int e = 0; e < 16; ++e) Kt[(part * 16 + e) * 64 + pjt] = f2bf(y[e] * ktl);
;       } else {
; #pragma unroll
;         for (int e4 = 0; e4 < 4; ++e4) { f32x4 v = {y[4 * e4], y[4 * e4 + 1], y[4 * e4 + 2], y[4 * e4 + 3]}; *(f32x4*)(vf + t * 128 + part * 16 + 4 * e4) = v; }
;       }
;     }
;     { const int cb = C_AZ + hh * 128 + part * 16; const u32x4 v0 = *(const u32x4*)(proj + (size_t)tabs * DINP + cb), v1 = *(const u32x4*)(proj + (size_t)tabs * DINP + cb + 8);
	v_lshlrev_b32_e32 v6, 16, v10
	v_pk_fma_f32 v[2:3], v[26:27], v[6:7], v[2:3]
	v_lshlrev_b32_e32 v6, 16, v14
	v_and_b32_e32 v7, 0xffff0000, v14
	v_pk_fma_f32 v[2:3], v[16:17], v[6:7], v[2:3]
	v_and_b32_e32 v121, 0xffff0000, v101
	v_pk_mul_f32 v[76:77], v[64:65], v[76:77] op_sel_hi:[0,1]
	v_lshlrev_b32_e32 v100, 16, v111
	v_and_b32_e32 v101, 0xffff0000, v111
	v_mul_f32_e32 v6, 0xbfb8aa3b, v3
	v_pk_mul_f32 v[116:117], v[64:65], v[116:117] op_sel_hi:[0,1]
	v_pk_mul_f32 v[114:115], v[64:65], v[114:115] op_sel_hi:[0,1]
	v_lshlrev_b32_e32 v66, 16, v113
	v_and_b32_e32 v67, 0xffff0000, v113
	v_pk_fma_f32 v[68:69], v[108:109], v[120:121], v[68:69]
	v_lshlrev_b32_e32 v72, 16, v112
	v_and_b32_e32 v73, 0xffff0000, v112
	v_pk_fma_f32 v[74:75], v[76:77], v[100:101], v[74:75]
	v_exp_f32_e32 v6, v6
	v_pk_fma_f32 v[66:67], v[116:117], v[66:67], v[68:69]
	v_pk_fma_f32 v[70:71], v[114:115], v[72:73], v[70:71]
	v_mul_f32_e32 v76, 0xbfb8aa3b, v75
	v_mul_f32_e32 v80, 0xbfb8aa3b, v79
	v_mul_f32_e32 v68, 0xbfb8aa3b, v67
	v_mul_f32_e32 v72, 0xbfb8aa3b, v71
	v_exp_f32_e32 v76, v76
	v_exp_f32_e32 v80, v80
	v_exp_f32_e32 v68, v68
	v_exp_f32_e32 v72, v72
	v_add_f32_e32 v6, 1.0, v6
	v_rcp_f32_e32 v7, v6
	v_mul_f32_e32 v6, 0xbfb8aa3b, v2
	v_add_f32_e32 v76, 1.0, v76
	v_add_f32_e32 v80, 1.0, v80
	v_exp_f32_e32 v6, v6
	v_add_f32_e32 v68, 1.0, v68
	v_add_f32_e32 v72, 1.0, v72
	v_rcp_f32_e32 v77, v76
	v_mul_f32_e32 v76, 0xbfb8aa3b, v74
	v_rcp_f32_e32 v81, v80
	v_mul_f32_e32 v80, 0xbfb8aa3b, v78
	v_rcp_f32_e32 v69, v68
	v_mul_f32_e32 v68, 0xbfb8aa3b, v66
	v_rcp_f32_e32 v73, v72
	v_mul_f32_e32 v72, 0xbfb8aa3b, v70
	v_exp_f32_e32 v76, v76
	v_exp_f32_e32 v80, v80
	v_exp_f32_e32 v68, v68
	v_exp_f32_e32 v72, v72
	v_add_f32_e32 v6, 1.0, v6
	v_rcp_f32_e32 v6, v6
	v_add_f32_e32 v76, 1.0, v76
	v_add_f32_e32 v80, 1.0, v80
	v_add_f32_e32 v68, 1.0, v68
	v_add_f32_e32 v72, 1.0, v72
	v_rcp_f32_e32 v76, v76
	v_rcp_f32_e32 v80, v80
	v_rcp_f32_e32 v68, v68
	v_rcp_f32_e32 v72, v72
	v_pk_mul_f32 v[2:3], v[2:3], v[6:7]
	v_pk_mul_f32 v[4:5], v[4:5], v[20:21]
	ds_write_b128 v83, v[2:5]
	v_pk_mul_f32 v[2:3], v[8:9], v[12:13]
	v_pk_mul_f32 v[4:5], v[36:37], v[40:41]
	ds_write_b128 v83, v[2:5] offset:16
	v_pk_mul_f32 v[2:3], v[78:79], v[80:81]
	v_pk_mul_f32 v[4:5], v[74:75], v[76:77]
	ds_write_b128 v83, v[2:5] offset:32
	v_pk_mul_f32 v[2:3], v[70:71], v[72:73]
	v_pk_mul_f32 v[4:5], v[66:67], v[68:69]
	ds_write_b128 v83, v[2:5] offset:48
	v_mad_i64_i32 v[2:3], s[2:3], v65, s81, v[56:57]
	v_lshl_add_u64 v[2:3], v[2:3], 0, v[0:1]
	v_add_co_u32_e32 v6, vcc, s82, v2
	s_mov_b64 s[2:3], 0x232e8000
	s_nop 0
	v_addc_co_u32_e32 v7, vcc, 0, v3, vcc
	global_load_dwordx4 v[2:5], v[6:7], off offset:2048
	s_nop 0
	global_load_dwordx4 v[6:9], v[6:7], off offset:2064
	v_lshrrev_b32_e32 v28, 2, v82
	v_and_b32_e32 v29, 32, v28
	s_waitcnt vmcnt(0) lgkmcnt(0)
; DI bf16_t f2bf(float x) { return (bf16_t)(pack2(x, 0.f) & 0xffffu); }
; DI void unpack8(const u32x4& v, float* f) { f[0] = bflo(v.x); f[1] = bfhi(v.x); f[2] = bflo(v.y); f[3] = bfhi(v.y); f[4] = bflo(v.z); f[5] = bfhi(v.z); f[6] = bflo(v.w); f[7] = bfhi(v.w); }
; DI float silu_f(float x) { return x * __builtin_amdgcn_rcpf(1.f + __expf(-x)); }
; DI int crow(int r, int h) { return (r & 3) + 8 * (r >> 2) + 4 * h; }
; #define MFMA32(a, b, c) __builtin_amdgcn_mfma_f32_32x32x16_bf16((a), (b), (c), 0, 0, 0)
; DI void gdn_prep_item(const Params& P, int l, int n, int hh, char* smem) {
;     ...
;     { const int cb = C_AZ + hh * 128 + part * 16; const u32x4 v0 = *(const u32x4*)(proj + (size_t)tabs * DINP + cb), v1 = *(const u32x4*)(proj + (size_t)tabs * DINP + cb + 8);
;       float zv[16]; unpack8(v0, zv); unpack8(v1, zv + 8);
; #pragma unroll
;       for (int e = 0; e < 16; ++e) Zt[(part * 16 + e) * 64 + t] = f2bf(silu_f(zv[e])); }
;   }
;   __syncthreads();
;   {
;     const int which = w >> 2, ti = (w >> 1) & 1, tj = w & 1; const char* Ab = which ? qb16 : kb16;
;     f32x16 acc;
; #pragma unroll
;     for (int r = 0; r < 16; ++r) acc[r] = 0.f;
; #pragma unroll
;     for (int s = 0; s < 8; ++s) { const bf16x8 a = *(const bf16x8*)(Ab + (32 * ti + lq) * 272 + (16 * s + 8 * h) * 2), b = *(const bf16x8*)(kb16 + (32 * tj + lq) * 272 + (16 * s + 8 * h) * 2);
;       acc = MFMA32(a, b, acc); }
;     const int j = 32 * tj + lq; const float gj = gcs[j]; const int pj = 32 * (j >> 5) + perm32(j & 31);
; #pragma unroll
;     for (int r = 0; r < 16; ++r) { const int i = 32 * ti + crow(r, h); const float dec = __expf(fminf(gcs[i] - gj, 0.f));
;       if (which == 0) Lm[i * 64 + j] = (j < i) ? gcs[64 + i] * acc[r] * dec : 0.f;
;       else QK[i * 64 + pj] = f2bf((j <= i) ? acc[r] * dec : 0.f); }
	v_lshlrev_b32_e32 v10, 16, v2
	v_and_b32_e32 v11, 0xffff0000, v2
	v_mul_f32_e32 v2, 0xbfb8aa3b, v10
	v_exp_f32_e32 v2, v2
	v_lshlrev_b32_e32 v16, 16, v5
	v_and_b32_e32 v17, 0xffff0000, v5
	v_lshlrev_b32_e32 v22, 16, v8
	v_add_f32_e32 v2, 1.0, v2
	v_rcp_f32_e32 v2, v2
	v_and_b32_e32 v5, 0xffff0000, v8
	v_lshlrev_b32_e32 v12, 16, v3
	v_and_b32_e32 v13, 0xffff0000, v3
	v_mul_f32_e32 v2, v2, v10
	v_cvt_pk_bf16_f32 v8, v2, s0
	v_add_u32_e32 v2, v84, v63
	v_ashrrev_i32_e32 v3, 31, v2
	v_lshlrev_b32_e32 v18, 16, v6
	v_and_b32_e32 v19, 0xffff0000, v6
	v_lshlrev_b32_e32 v20, 16, v7
	v_and_b32_e32 v21, 0xffff0000, v7
	v_lshl_add_u64 v[6:7], v[2:3], 1, v[54:55]
	v_lshl_add_u64 v[2:3], v[6:7], 0, s[2:3]
	s_mov_b32 s2, 0x232e8000
	v_add_co_u32_e32 v6, vcc, s2, v6
	v_lshlrev_b32_e32 v14, 16, v4
	s_nop 0
	v_addc_co_u32_e32 v7, vcc, 0, v7, vcc
	global_store_short v[6:7], v8, off
	v_mul_f32_e32 v6, 0xbfb8aa3b, v11
	v_exp_f32_e32 v6, v6
	v_and_b32_e32 v15, 0xffff0000, v4
	v_lshlrev_b32_e32 v4, 16, v9
	v_and_b32_e32 v0, 0xffff0000, v9
	v_add_f32_e32 v6, 1.0, v6
	v_rcp_f32_e32 v6, v6
	s_movk_i32 s2, 0xff
	v_cmp_lt_u32_e32 vcc, s2, v82
	v_cmp_gt_u32_e64 s[2:3], s97, v82
	v_mul_f32_e32 v6, v6, v11
	v_cvt_pk_bf16_f32 v6, v6, s0
	global_store_short v[2:3], v6, off offset:128
	v_mul_f32_e32 v6, 0xbfb8aa3b, v12
	v_exp_f32_e32 v6, v6
	s_nop 0
	v_add_f32_e32 v6, 1.0, v6
	v_rcp_f32_e32 v6, v6
	s_nop 0
	v_mul_f32_e32 v6, v6, v12
	v_cvt_pk_bf16_f32 v6, v6, s0
	global_store_short v[2:3], v6, off offset:256
	v_mul_f32_e32 v6, 0xbfb8aa3b, v13
	v_exp_f32_e32 v6, v6
	s_nop 0
	v_add_f32_e32 v6, 1.0, v6
	v_rcp_f32_e32 v6, v6
	s_nop 0
	v_mul_f32_e32 v6, v6, v13
	v_cvt_pk_bf16_f32 v6, v6, s0
	global_store_short v[2:3], v6, off offset:384
	v_mul_f32_e32 v6, 0xbfb8aa3b, v14
	v_exp_f32_e32 v6, v6
	s_nop 0
	v_add_f32_e32 v6, 1.0, v6
	v_rcp_f32_e32 v6, v6
	s_nop 0
	v_mul_f32_e32 v6, v6, v14
	v_cvt_pk_bf16_f32 v6, v6, s0
	global_store_short v[2:3], v6, off offset:512
	v_mul_f32_e32 v6, 0xbfb8aa3b, v15
	v_exp_f32_e32 v6, v6
	s_nop 0
	v_add_f32_e32 v6, 1.0, v6
	v_rcp_f32_e32 v6, v6
	s_nop 0
	v_mul_f32_e32 v6, v6, v15
	v_cvt_pk_bf16_f32 v6, v6, s0
	global_store_short v[2:3], v6, off offset:640
	v_mul_f32_e32 v6, 0xbfb8aa3b, v16
	v_exp_f32_e32 v6, v6
	s_nop 0
	v_add_f32_e32 v6, 1.0, v6
	v_rcp_f32_e32 v6, v6
	s_nop 0
	v_mul_f32_e32 v6, v6, v16
	v_cvt_pk_bf16_f32 v6, v6, s0
	global_store_short v[2:3], v6, off offset:768
	v_mul_f32_e32 v6, 0xbfb8aa3b, v17
	v_exp_f32_e32 v6, v6
	s_nop 0
	v_add_f32_e32 v6, 1.0, v6
	v_rcp_f32_e32 v6, v6
	s_nop 0
	v_mul_f32_e32 v6, v6, v17
	v_cvt_pk_bf16_f32 v6, v6, s0
	global_store_short v[2:3], v6, off offset:896
	v_mul_f32_e32 v6, 0xbfb8aa3b, v18
	v_exp_f32_e32 v6, v6
	s_nop 0
	v_add_f32_e32 v6, 1.0, v6
	v_rcp_f32_e32 v6, v6
	s_nop 0
	v_mul_f32_e32 v6, v6, v18
	v_cvt_pk_bf16_f32 v6, v6, s0
	global_store_short v[2:3], v6, off offset:1024
	v_mul_f32_e32 v6, 0xbfb8aa3b, v19
	v_exp_f32_e32 v6, v6
	s_nop 0
	v_add_f32_e32 v6, 1.0, v6
	v_rcp_f32_e32 v6, v6
	s_nop 0
	v_mul_f32_e32 v6, v6, v19
	v_cvt_pk_bf16_f32 v6, v6, s0
	global_store_short v[2:3], v6, off offset:1152
	v_mul_f32_e32 v6, 0xbfb8aa3b, v20
	v_exp_f32_e32 v6, v6
	s_nop 0
	v_add_f32_e32 v6, 1.0, v6
	v_rcp_f32_e32 v6, v6
	s_nop 0
	v_mul_f32_e32 v6, v6, v20
	v_cvt_pk_bf16_f32 v6, v6, s0
	global_store_short v[2:3], v6, off offset:1280
	v_mul_f32_e32 v6, 0xbfb8aa3b, v21
	v_exp_f32_e32 v6, v6
	s_nop 0
	v_add_f32_e32 v6, 1.0, v6
	v_rcp_f32_e32 v6, v6
	s_nop 0
	v_mul_f32_e32 v6, v6, v21
	v_cvt_pk_bf16_f32 v6, v6, s0
	global_store_short v[2:3], v6, off offset:1408
	v_mul_f32_e32 v6, 0xbfb8aa3b, v22
	v_exp_f32_e32 v6, v6
	s_nop 0
	v_add_f32_e32 v6, 1.0, v6
	v_rcp_f32_e32 v6, v6
	s_nop 0
	v_mul_f32_e32 v6, v6, v22
	v_cvt_pk_bf16_f32 v6, v6, s0
	global_store_short v[2:3], v6, off offset:1536
	v_mul_f32_e32 v6, 0xbfb8aa3b, v5
	v_exp_f32_e32 v6, v6
	s_nop 0
	v_add_f32_e32 v6, 1.0, v6
	v_rcp_f32_e32 v6, v6
	s_nop 0
	v_mul_f32_e32 v5, v6, v5
	v_cvt_pk_bf16_f32 v5, v5, s0
	global_store_short v[2:3], v5, off offset:1664
	v_mul_f32_e32 v5, 0xbfb8aa3b, v4
	v_exp_f32_e32 v5, v5
	s_nop 0
	v_add_f32_e32 v5, 1.0, v5
	v_rcp_f32_e32 v5, v5
	s_nop 0
	v_mul_f32_e32 v4, v5, v4
	v_cvt_pk_bf16_f32 v4, v4, s0
	global_store_short v[2:3], v4, off offset:1792
	v_mul_f32_e32 v4, 0xbfb8aa3b, v0
	v_exp_f32_e32 v4, v4
	s_nop 0
	v_add_f32_e32 v4, 1.0, v4
	v_rcp_f32_e32 v4, v4
	s_nop 0
	v_mul_f32_e32 v0, v4, v0
	v_cvt_pk_bf16_f32 v0, v0, s0
	global_store_short v[2:3], v0, off offset:1920
	v_mov_b32_e32 v0, 0x4400
	v_or_b32_e32 v2, v29, v61
	v_lshrrev_b32_e32 v4, 1, v82
	v_cndmask_b32_e64 v0, v0, 0, s[2:3]
	v_mul_u32_u24_e32 v2, 0x110, v2
	v_lshlrev_b32_e32 v3, 4, v59
	v_and_b32_e32 v19, 32, v4
	v_or_b32_e32 v18, v19, v61
	v_add3_u32 v0, v0, v2, v3
	s_waitcnt lgkmcnt(0)
	s_barrier
	v_mad_u32_u24 v30, v18, s11, v3
	ds_read_b128 v[2:5], v0
	ds_read_b128 v[20:23], v0 offset:32
	ds_read_b128 v[6:9], v30
	ds_read_b128 v[24:27], v30 offset:32
	s_waitcnt lgkmcnt(0)
	v_mfma_f32_32x32x16_bf16 v[2:17], v[2:5], v[6:9], 0
	v_mfma_f32_32x32x16_bf16 v[2:17], v[20:23], v[24:27], v[2:17]
	ds_read_b128 v[20:23], v0 offset:64
	ds_read_b128 v[24:27], v30 offset:64
	s_waitcnt lgkmcnt(0)
	v_mfma_f32_32x32x16_bf16 v[2:17], v[20:23], v[24:27], v[2:17]
	ds_read_b128 v[20:23], v0 offset:96
	ds_read_b128 v[24:27], v30 offset:96
	s_waitcnt lgkmcnt(0)
	v_mfma_f32_32x32x16_bf16 v[2:17], v[20:23], v[24:27], v[2:17]
	ds_read_b128 v[20:23], v0 offset:128
	ds_read_b128 v[24:27], v30 offset:128
	s_waitcnt lgkmcnt(0)
	v_mfma_f32_32x32x16_bf16 v[2:17], v[20:23], v[24:27], v[2:17]
	ds_read_b128 v[20:23], v0 offset:160
	ds_read_b128 v[24:27], v30 offset:160
	s_waitcnt lgkmcnt(0)
	v_mfma_f32_32x32x16_bf16 v[2:17], v[20:23], v[24:27], v[2:17]
	ds_read_b128 v[20:23], v0 offset:192
	ds_read_b128 v[24:27], v30 offset:192
	s_waitcnt lgkmcnt(0)
	v_mfma_f32_32x32x16_bf16 v[2:17], v[20:23], v[24:27], v[2:17]
	ds_read_b128 v[20:23], v0 offset:224
	ds_read_b128 v[24:27], v30 offset:224
	s_waitcnt lgkmcnt(0)
	v_mfma_f32_32x32x16_bf16 v[2:17], v[20:23], v[24:27], v[2:17]
	v_lshlrev_b32_e32 v22, 2, v18
	v_or_b32_e32 v0, 0x1c800, v22
	ds_read_b32 v20, v0
	v_lshlrev_b32_e32 v0, 1, v82
	v_and_b32_e32 v0, 24, v0
	v_and_b32_e32 v21, 4, v28
	v_and_b32_e32 v23, 3, v82
	v_or3_b32 v68, v21, v23, v0
	v_lshl_or_b32 v21, v59, 2, v29
	v_lshl_or_b32 v0, v21, 2, v241
	ds_read_b32 v23, v0
	s_waitcnt lgkmcnt(0)
	v_sub_f32_e32 v23, v23, v20
	v_min_f32_e32 v23, 0, v23
	v_mul_f32_e32 v23, 0x3fb8aa3b, v23
	v_exp_f32_e32 v23, v23
	s_and_saveexec_b64 s[2:3], vcc
	s_xor_b64 s[10:11], exec, s[2:3]
	s_cbranch_execz .LBB0_433
	v_mul_f32_e32 v0, v2, v23
	v_cvt_pk_bf16_f32 v0, v0, s0
	v_cmp_le_u32_e64 s[2:3], v18, v21
	s_nop 1
	v_cndmask_b32_e64 v23, 0, v0, s[2:3]
	v_lshlrev_b32_e32 v0, 6, v21
	v_or3_b32 v0, v0, v19, v68
	v_lshlrev_b32_e32 v0, 1, v0
	v_lshl_add_u64 v[24:25], v[52:53], 0, v[0:1]
	global_store_short v[24:25], v23, off
